# K_FFN epilogue body hand-generated: DPP row rotates/shifts for the conv neighbours, packed rcp/exp via SDWA preserve, bias folded into the conv fma chain, two column pairs in flight (1064 vs ~1540 ins
# speedup vs baseline: 1.0067x; 1.0067x over previous
; #define LAS __attribute__((address_space(3)))
;     __device__ __forceinline__ void operator()(const f32x4 (&acc)[2][2][4][2], const GUnit& u, int wr, int wc, int fr, int fq, LAS unsigned char* lds) const {
;     ...
;             f16x2 w0p[4], w1p[4], w2p[4], bbp[4];
; #pragma unroll
;             for (int n = 0; n < 2; ++n) { const f32x4 a0 = *(const f32x4*)(cw + fb + 4 * n), a1 = *(const f32x4*)(cw + DFF + fb + 4 * n), a2 = *(const f32x4*)(cw + 2 * DFF + fb + 4 * n), ab = *(const f32x4*)(cb + fb + 4 * n);
; #pragma unroll
;                 for (int q = 0; q < 2; ++q) { w0p[2 * n + q] = (f16x2){(f16)a0[2 * q], (f16)a0[2 * q + 1]}; w1p[2 * n + q] = (f16x2){(f16)a1[2 * q], (f16)a1[2 * q + 1]};
;                                               w2p[2 * n + q] = (f16x2){(f16)a2[2 * q], (f16)a2[2 * q + 1]}; bbp[2 * n + q] = (f16x2){(f16)ab[2 * q], (f16)ab[2 * q + 1]}; } }
; #pragma unroll
;             for (int ai = 0; ai < 2; ++ai) { const int c = 2 * ai + wr;
;                 unsigned gp[4][4], eup[4], edp[4];
; #pragma unroll
;                 for (int m = 0; m < 4; ++m)
; #pragma unroll
;                     for (int n = 0; n < 2; ++n)
; #pragma unroll
;                         for (int q = 0; q < 2; ++q) gp[m][2 * n + q] = pk_f16(acc[ai][1][m][n][2 * q], acc[ai][1][m][n][2 * q + 1]);
; #pragma unroll
;                 for (int n = 0; n < 2; ++n) {
;                     const f32x4 eu = c > 0 ? *(const LAS f32x4*)(EL + ((c - 1) * 2 + 1) * 128 + wc * 32 + 8 * fqL + 4 * n) : (f32x4){0.f, 0.f, 0.f, 0.f};
;                     const f32x4 ed = c < 3 ? *(const LAS f32x4*)(EL + ((c + 1) * 2 + 0) * 128 + wc * 32 + 8 * fqL + 4 * n) : (f32x4){0.f, 0.f, 0.f, 0.f};
; #pragma unroll
;                     for (int q = 0; q < 2; ++q) { eup[2 * n + q] = pk_f16(eu[2 * q], eu[2 * q + 1]); edp[2 * n + q] = pk_f16(ed[2 * q], ed[2 * q + 1]); } }
; #pragma unroll
;                 for (int m = 0; m < 4; ++m) {
;                     u32x4 UP, DN, GG;
; #pragma unroll
;                     for (int j = 0; j < 4; ++j) { const int g = (int)gp[m][j];
;                         const int oldu = m > 0 ? shl_((int)gp[m > 0 ? m - 1 : 0][j], lane15) : (int)eup[j];
;                         const int ups = __builtin_amdgcn_update_dpp(0, g, 0x111, 0xf, 0xf, true);
;                         const int oldd = m < 3 ? shl_((int)gp[m < 3 ? m + 1 : 3][j], lane0r) : (int)edp[j];
.LBB0_264:
	s_waitcnt vmcnt(0)
	v_cvt_pk_f16_f32 v164, v164, v165
	v_cvt_pk_f16_f32 v165, v166, v167
	v_cvt_pk_f16_f32 v166, v168, v169
	v_cvt_pk_f16_f32 v167, v170, v171
	v_cvt_pk_f16_f32 v168, v156, v157
	v_cvt_pk_f16_f32 v169, v158, v159
	v_cvt_pk_f16_f32 v170, v160, v161
	v_cvt_pk_f16_f32 v171, v162, v163
	v_cvt_pk_f16_f32 v156, v148, v149
	v_cvt_pk_f16_f32 v157, v150, v151
	v_cvt_pk_f16_f32 v158, v152, v153
	v_cvt_pk_f16_f32 v159, v154, v155
	v_cvt_pk_f16_f32 v160, v140, v141
	v_cvt_pk_f16_f32 v161, v142, v143
	v_cvt_pk_f16_f32 v162, v144, v145
	v_cvt_pk_f16_f32 v163, v146, v147
	s_movk_i32 s45, 0x336a
	s_movk_i32 s55, 0x383f
	s_movk_i32 s65, 0x39b0
	s_mov_b32 s68, 0xb08d
	s_movk_i32 s69, 0x3014
	s_mov_b32 s72, 0xb9c5
	v_cmp_eq_u32_e64 s[8:9], 15, v32
	v_cmp_eq_u32_e64 s[10:11], 0, v32
	s_lshl_b32 s29, s37, 8
	s_add_i32 s29, s29, s48
	v_readlane_b32 s12, v253, 13
	v_readlane_b32 s13, v253, 14
	v_add_u32_e32 v32, s29, v32
	s_movk_i32 s29, 0x1600
	s_and_b32 s36, s37, 7
	v_lshl_add_u64 v[192:193], v[190:191], 1, s[12:13]
	s_waitcnt lgkmcnt(0)
	v_cvt_pk_f16_f32 v172, v172, v173
	v_cvt_pk_f16_f32 v173, v174, v175
	v_cvt_pk_f16_f32 v174, v176, v177
	v_cvt_pk_f16_f32 v175, v178, v179
	v_cvt_pk_f16_f32 v132, v132, v133
	v_cvt_pk_f16_f32 v133, v134, v135
	v_cvt_pk_f16_f32 v134, v136, v137
	v_cvt_pk_f16_f32 v135, v138, v139
	v_cvt_pk_f16_f32 v140, v120, v121
	v_cvt_pk_f16_f32 v141, v122, v123
	v_cvt_pk_f16_f32 v142, v116, v117
	v_cvt_pk_f16_f32 v143, v118, v119
	v_cvt_pk_f16_f32 v144, v104, v105
	v_cvt_pk_f16_f32 v145, v106, v107
	v_cvt_pk_f16_f32 v146, v100, v101
	v_cvt_pk_f16_f32 v147, v102, v103
	v_mov_b32_dpp v172, v140 row_shr:1 row_mask:0xf bank_mask:0xf
	v_mov_b32_dpp v174, v142 row_shr:1 row_mask:0xf bank_mask:0xf
	v_mov_b32_dpp v138, v144 row_ror:15 row_mask:0xf bank_mask:0xf
	v_mov_b32_dpp v178, v146 row_ror:15 row_mask:0xf bank_mask:0xf
	v_mov_b32_dpp v138, v140 row_shl:1 row_mask:0xf bank_mask:0xf
	v_mov_b32_dpp v178, v142 row_shl:1 row_mask:0xf bank_mask:0xf
	v_pk_fma_f16 v136, v172, v164, v160
	v_pk_fma_f16 v176, v174, v166, v162
	v_pk_fma_f16 v136, v140, v168, v136
	v_pk_fma_f16 v176, v142, v170, v176
	v_pk_fma_f16 v136, v138, v156, v136
	v_pk_fma_f16 v176, v178, v158, v176
	v_mov_b32_dpp v173, v141 row_shr:1 row_mask:0xf bank_mask:0xf
	v_mov_b32_dpp v175, v143 row_shr:1 row_mask:0xf bank_mask:0xf
	v_mov_b32_dpp v139, v145 row_ror:15 row_mask:0xf bank_mask:0xf
	v_mov_b32_dpp v179, v147 row_ror:15 row_mask:0xf bank_mask:0xf
	v_mov_b32_dpp v139, v141 row_shl:1 row_mask:0xf bank_mask:0xf
	v_mov_b32_dpp v179, v143 row_shl:1 row_mask:0xf bank_mask:0xf
	v_pk_fma_f16 v137, v173, v165, v161
	v_pk_fma_f16 v177, v175, v167, v163
	v_pk_fma_f16 v137, v141, v169, v137
	v_pk_fma_f16 v177, v143, v171, v177
	v_pk_fma_f16 v137, v139, v157, v137
	v_pk_fma_f16 v177, v179, v159, v177
	s_cmp_eq_u32 s48, 0
	s_cbranch_scc0 .Lffn_side_top_skip
	s_cmp_lg_u32 s36, 0
	s_cbranch_scc0 .Lffn_side_top_skip
	s_and_saveexec_b64 s[80:81], s[10:11]
	s_lshl_b32 s12, s37, 1
	v_mov_b32_e32 v152, 0xb00
	v_mad_i64_i32 v[152:153], vcc, s12, v152, v[190:191]
	v_readlane_b32 s12, v251, 22
	v_readlane_b32 s13, v251, 23
	v_lshlrev_b64 v[152:153], 2, v[152:153]
	s_nop 1
	v_lshl_add_u64 v[154:155], s[12:13], 0, v[152:153]
	global_store_dwordx2 v[154:155], v[120:121], off
	global_store_dwordx2 v[154:155], v[122:123], off offset:8
	global_store_dwordx2 v[154:155], v[116:117], off offset:16
	global_store_dwordx2 v[154:155], v[118:119], off offset:24
	v_readlane_b32 s12, v251, 24
	v_readlane_b32 s13, v251, 25
	v_cvt_f32_f16_e32 v138, v136
	v_cvt_f32_f16_sdwa v139, v136 dst_sel:DWORD dst_unused:UNUSED_PAD src0_sel:WORD_1
	v_lshl_add_u64 v[154:155], s[12:13], 0, v[152:153]
	global_store_dwordx2 v[154:155], v[138:139], off
	v_cvt_f32_f16_e32 v178, v137
	v_cvt_f32_f16_sdwa v179, v137 dst_sel:DWORD dst_unused:UNUSED_PAD src0_sel:WORD_1
	s_nop 0
	global_store_dwordx2 v[154:155], v[178:179], off offset:8
	v_cvt_f32_f16_e32 v138, v176
	v_cvt_f32_f16_sdwa v139, v176 dst_sel:DWORD dst_unused:UNUSED_PAD src0_sel:WORD_1
	s_nop 0
	global_store_dwordx2 v[154:155], v[138:139], off offset:16
	v_cvt_f32_f16_e32 v178, v177
	v_cvt_f32_f16_sdwa v179, v177 dst_sel:DWORD dst_unused:UNUSED_PAD src0_sel:WORD_1
	s_nop 0
	global_store_dwordx2 v[154:155], v[178:179], off offset:24
	v_readlane_b32 s12, v251, 26
	v_readlane_b32 s13, v251, 27
	s_nop 3
	v_lshl_add_u64 v[154:155], s[12:13], 0, v[152:153]
	global_store_dwordx2 v[154:155], v[128:129], off
	global_store_dwordx2 v[154:155], v[130:131], off offset:8
	global_store_dwordx2 v[154:155], v[124:125], off offset:16
	global_store_dwordx2 v[154:155], v[126:127], off offset:24
	s_or_b64 exec, exec, s[80:81]
; __device__ __forceinline__ int shl_(int v, int src_lane) { return __builtin_amdgcn_ds_bpermute(src_lane << 2, v); }
;     __device__ __forceinline__ void operator()(const f32x4 (&acc)[2][2][4][2], const GUnit& u, int wr, int wc, int fr, int fq, LAS unsigned char* lds) const {
;     ...
;                 for (int m = 0; m < 4; ++m) {
;                     u32x4 UP, DN, GG;
; #pragma unroll
;                     for (int j = 0; j < 4; ++j) { const int g = (int)gp[m][j];
;                         const int oldu = m > 0 ? shl_((int)gp[m > 0 ? m - 1 : 0][j], lane15) : (int)eup[j];
;                         const int ups = __builtin_amdgcn_update_dpp(0, g, 0x111, 0xf, 0xf, true);
;                         const int oldd = m < 3 ? shl_((int)gp[m < 3 ? m + 1 : 3][j], lane0r) : (int)edp[j];
;                         const int dns = __builtin_amdgcn_update_dpp(0, g, 0x101, 0xf, 0xf, true);
;                         UP[j] = (unsigned)(frL == 0 ? oldu : ups); DN[j] = (unsigned)(frL == 15 ? oldd : dns); GG[j] = (unsigned)g; }
;                     const f16x8 uph = __builtin_bit_cast(f16x8, UP), dnh = __builtin_bit_cast(f16x8, DN), ggh = __builtin_bit_cast(f16x8, GG);
;                     f16x2 yv[4];
;                     yv[0] = __builtin_shufflevector(uph, uph, 0, 1) * w0p[0] + __builtin_shufflevector(ggh, ggh, 0, 1) * w1p[0] + __builtin_shufflevector(dnh, dnh, 0, 1) * w2p[0] + bbp[0];
;                     yv[1] = __builtin_shufflevector(uph, uph, 2, 3) * w0p[1] + __builtin_shufflevector(ggh, ggh, 2, 3) * w1p[1] + __builtin_shufflevector(dnh, dnh, 2, 3) * w2p[1] + bbp[1];
;                     yv[2] = __builtin_shufflevector(uph, uph, 4, 5) * w0p[2] + __builtin_shufflevector(ggh, ggh, 4, 5) * w1p[2] + __builtin_shufflevector(dnh, dnh, 4, 5) * w2p[2] + bbp[2];
;                     yv[3] = __builtin_shufflevector(uph, uph, 6, 7) * w0p[3] + __builtin_shufflevector(ggh, ggh, 6, 7) * w1p[3] + __builtin_shufflevector(dnh, dnh, 6, 7) * w2p[3] + bbp[3];
;                     u32x4 o;
; #pragma unroll
;                     for (int n = 0; n < 2; ++n)
; #pragma unroll
;                         for (int q = 0; q < 2; ++q) { const int j = 2 * n + q;
.Lffn_side_top_skip:
	v_and_b32_e32 v138, 0x7fff7fff, v136
	v_and_b32_e32 v178, 0x7fff7fff, v176
	v_pk_fma_f16 v139, v138, s45, 1.0 op_sel_hi:[1,0,0]
	v_pk_fma_f16 v179, v178, s45, 1.0 op_sel_hi:[1,0,0]
	v_rcp_f16_e32 v183, v139
	v_rcp_f16_e32 v189, v179
	v_rcp_f16_sdwa v183, v139 dst_sel:WORD_1 dst_unused:UNUSED_PRESERVE src0_sel:WORD_1
	v_rcp_f16_sdwa v189, v179 dst_sel:WORD_1 dst_unused:UNUSED_PRESERVE src0_sel:WORD_1
	v_pk_fma_f16 v139, v183, s55, v228 op_sel_hi:[1,0,0]
	v_pk_fma_f16 v179, v189, s55, v228 op_sel_hi:[1,0,0]
	v_pk_fma_f16 v139, v183, v139, s65 op_sel_hi:[1,1,0]
	v_pk_fma_f16 v179, v189, v179, s65 op_sel_hi:[1,1,0]
	v_pk_fma_f16 v139, v183, v139, s68 op_sel_hi:[1,1,0]
	v_pk_fma_f16 v179, v189, v179, s68 op_sel_hi:[1,1,0]
	v_pk_fma_f16 v139, v183, v139, s69 op_sel_hi:[1,1,0]
	v_pk_fma_f16 v179, v189, v179, s69 op_sel_hi:[1,1,0]
	v_pk_mul_f16 v139, v183, v139
	v_pk_mul_f16 v179, v189, v179
	v_pk_mul_f16 v183, v136, v136
	v_pk_mul_f16 v189, v176, v176
	v_pk_mul_f16 v183, v183, s72 op_sel_hi:[1,0]
	v_pk_mul_f16 v189, v189, s72 op_sel_hi:[1,0]
	v_exp_f16_e32 v153, v183
	v_exp_f16_e32 v155, v189
	v_exp_f16_sdwa v153, v183 dst_sel:WORD_1 dst_unused:UNUSED_PRESERVE src0_sel:WORD_1
	v_exp_f16_sdwa v155, v189 dst_sel:WORD_1 dst_unused:UNUSED_PRESERVE src0_sel:WORD_1
	v_pk_mul_f16 v139, v153, v139
	v_pk_mul_f16 v179, v155, v179
	v_pk_max_f16 v136, v136, 0
	v_pk_max_f16 v176, v176, 0
	v_pk_fma_f16 v136, v138, v139, v136 neg_lo:[1,0,0] neg_hi:[1,0,0]
	v_pk_fma_f16 v176, v178, v179, v176 neg_lo:[1,0,0] neg_hi:[1,0,0]
	v_cvt_pk_f16_f32 v183, v128, v129
	v_cvt_pk_f16_f32 v189, v124, v125
	v_pk_mul_f16 v152, v183, v136
	v_pk_mul_f16 v154, v189, v176
	v_add_u32_e32 v152, 0x40004, v152
	v_add_u32_e32 v154, 0x40004, v154
	v_and_b32_e32 v152, 0xfff8fff8, v152
	v_and_b32_e32 v154, 0xfff8fff8, v154
	v_and_b32_e32 v136, 0x7fff7fff, v137
	v_and_b32_e32 v176, 0x7fff7fff, v177
	v_pk_fma_f16 v138, v136, s45, 1.0 op_sel_hi:[1,0,0]
	v_pk_fma_f16 v178, v176, s45, 1.0 op_sel_hi:[1,0,0]
	v_rcp_f16_e32 v139, v138
	v_rcp_f16_e32 v179, v178
	v_rcp_f16_sdwa v139, v138 dst_sel:WORD_1 dst_unused:UNUSED_PRESERVE src0_sel:WORD_1
	v_rcp_f16_sdwa v179, v178 dst_sel:WORD_1 dst_unused:UNUSED_PRESERVE src0_sel:WORD_1
	v_pk_fma_f16 v138, v139, s55, v228 op_sel_hi:[1,0,0]
	v_pk_fma_f16 v178, v179, s55, v228 op_sel_hi:[1,0,0]
	v_pk_fma_f16 v138, v139, v138, s65 op_sel_hi:[1,1,0]
	v_pk_fma_f16 v178, v179, v178, s65 op_sel_hi:[1,1,0]
	v_pk_fma_f16 v138, v139, v138, s68 op_sel_hi:[1,1,0]
	v_pk_fma_f16 v178, v179, v178, s68 op_sel_hi:[1,1,0]
	v_pk_fma_f16 v138, v139, v138, s69 op_sel_hi:[1,1,0]
	v_pk_fma_f16 v178, v179, v178, s69 op_sel_hi:[1,1,0]
	v_pk_mul_f16 v138, v139, v138
	v_pk_mul_f16 v178, v179, v178
	v_pk_mul_f16 v139, v137, v137
	v_pk_mul_f16 v179, v177, v177
	v_pk_mul_f16 v139, v139, s72 op_sel_hi:[1,0]
	v_pk_mul_f16 v179, v179, s72 op_sel_hi:[1,0]
	v_exp_f16_e32 v183, v139
	v_exp_f16_e32 v189, v179
	v_exp_f16_sdwa v183, v139 dst_sel:WORD_1 dst_unused:UNUSED_PRESERVE src0_sel:WORD_1
	v_exp_f16_sdwa v189, v179 dst_sel:WORD_1 dst_unused:UNUSED_PRESERVE src0_sel:WORD_1
	v_pk_mul_f16 v138, v183, v138
	v_pk_mul_f16 v178, v189, v178
	v_pk_max_f16 v137, v137, 0
	v_pk_max_f16 v177, v177, 0
	v_pk_fma_f16 v137, v136, v138, v137 neg_lo:[1,0,0] neg_hi:[1,0,0]
	v_pk_fma_f16 v177, v176, v178, v177 neg_lo:[1,0,0] neg_hi:[1,0,0]
	v_cvt_pk_f16_f32 v139, v130, v131
	v_cvt_pk_f16_f32 v179, v126, v127
	v_pk_mul_f16 v153, v139, v137
	v_pk_mul_f16 v155, v179, v177
	v_add_u32_e32 v153, 0x40004, v153
	v_add_u32_e32 v155, 0x40004, v155
	v_and_b32_e32 v153, 0xfff8fff8, v153
	v_and_b32_e32 v155, 0xfff8fff8, v155
	v_mad_i64_i32 v[194:195], vcc, v32, s29, v[192:193]
	global_store_dwordx4 v[194:195], v[152:155], off
	v_cvt_pk_f16_f32 v148, v88, v89
	v_cvt_pk_f16_f32 v149, v90, v91
	v_cvt_pk_f16_f32 v150, v84, v85
	v_cvt_pk_f16_f32 v151, v86, v87
	v_mov_b32_dpp v136, v140 row_ror:1 row_mask:0xf bank_mask:0xf
	v_mov_b32_dpp v176, v141 row_ror:1 row_mask:0xf bank_mask:0xf
	v_mov_b32_dpp v136, v144 row_shr:1 row_mask:0xf bank_mask:0xf
	v_mov_b32_dpp v176, v145 row_shr:1 row_mask:0xf bank_mask:0xf
	v_mov_b32_dpp v137, v148 row_ror:15 row_mask:0xf bank_mask:0xf
	v_mov_b32_dpp v177, v149 row_ror:15 row_mask:0xf bank_mask:0xf
	v_mov_b32_dpp v137, v144 row_shl:1 row_mask:0xf bank_mask:0xf
	v_mov_b32_dpp v177, v145 row_shl:1 row_mask:0xf bank_mask:0xf
	v_pk_fma_f16 v136, v136, v164, v160
	v_pk_fma_f16 v176, v176, v165, v161
	v_pk_fma_f16 v136, v144, v168, v136
	v_pk_fma_f16 v176, v145, v169, v176
	v_pk_fma_f16 v136, v137, v156, v136
	v_pk_fma_f16 v176, v177, v157, v176
	v_and_b32_e32 v137, 0x7fff7fff, v136
	v_and_b32_e32 v177, 0x7fff7fff, v176
	v_pk_fma_f16 v138, v137, s45, 1.0 op_sel_hi:[1,0,0]
	v_pk_fma_f16 v178, v177, s45, 1.0 op_sel_hi:[1,0,0]
	v_rcp_f16_e32 v139, v138
	v_rcp_f16_e32 v179, v178
	v_rcp_f16_sdwa v139, v138 dst_sel:WORD_1 dst_unused:UNUSED_PRESERVE src0_sel:WORD_1
	v_rcp_f16_sdwa v179, v178 dst_sel:WORD_1 dst_unused:UNUSED_PRESERVE src0_sel:WORD_1
	v_pk_fma_f16 v138, v139, s55, v228 op_sel_hi:[1,0,0]
	v_pk_fma_f16 v178, v179, s55, v228 op_sel_hi:[1,0,0]
	v_pk_fma_f16 v138, v139, v138, s65 op_sel_hi:[1,1,0]
	v_pk_fma_f16 v178, v179, v178, s65 op_sel_hi:[1,1,0]
	v_pk_fma_f16 v138, v139, v138, s68 op_sel_hi:[1,1,0]
	v_pk_fma_f16 v178, v179, v178, s68 op_sel_hi:[1,1,0]
	v_pk_fma_f16 v138, v139, v138, s69 op_sel_hi:[1,1,0]
	v_pk_fma_f16 v178, v179, v178, s69 op_sel_hi:[1,1,0]
	v_pk_mul_f16 v138, v139, v138
	v_pk_mul_f16 v178, v179, v178
	v_pk_mul_f16 v139, v136, v136
	v_pk_mul_f16 v179, v176, v176
	v_pk_mul_f16 v139, v139, s72 op_sel_hi:[1,0]
	v_pk_mul_f16 v179, v179, s72 op_sel_hi:[1,0]
; __device__ __forceinline__ int shl_(int v, int src_lane) { return __builtin_amdgcn_ds_bpermute(src_lane << 2, v); }
;     __device__ __forceinline__ void operator()(const f32x4 (&acc)[2][2][4][2], const GUnit& u, int wr, int wc, int fr, int fq, LAS unsigned char* lds) const {
;     ...
;                 for (int m = 0; m < 4; ++m) {
;                     u32x4 UP, DN, GG;
; #pragma unroll
;                     for (int j = 0; j < 4; ++j) { const int g = (int)gp[m][j];
;                         const int oldu = m > 0 ? shl_((int)gp[m > 0 ? m - 1 : 0][j], lane15) : (int)eup[j];
;                         const int ups = __builtin_amdgcn_update_dpp(0, g, 0x111, 0xf, 0xf, true);
;                         const int oldd = m < 3 ? shl_((int)gp[m < 3 ? m + 1 : 3][j], lane0r) : (int)edp[j];
;                         const int dns = __builtin_amdgcn_update_dpp(0, g, 0x101, 0xf, 0xf, true);
;                         UP[j] = (unsigned)(frL == 0 ? oldu : ups); DN[j] = (unsigned)(frL == 15 ? oldd : dns); GG[j] = (unsigned)g; }
;                     const f16x8 uph = __builtin_bit_cast(f16x8, UP), dnh = __builtin_bit_cast(f16x8, DN), ggh = __builtin_bit_cast(f16x8, GG);
;                     f16x2 yv[4];
;                     yv[0] = __builtin_shufflevector(uph, uph, 0, 1) * w0p[0] + __builtin_shufflevector(ggh, ggh, 0, 1) * w1p[0] + __builtin_shufflevector(dnh, dnh, 0, 1) * w2p[0] + bbp[0];
;                     yv[1] = __builtin_shufflevector(uph, uph, 2, 3) * w0p[1] + __builtin_shufflevector(ggh, ggh, 2, 3) * w1p[1] + __builtin_shufflevector(dnh, dnh, 2, 3) * w2p[1] + bbp[1];
;                     yv[2] = __builtin_shufflevector(uph, uph, 4, 5) * w0p[2] + __builtin_shufflevector(ggh, ggh, 4, 5) * w1p[2] + __builtin_shufflevector(dnh, dnh, 4, 5) * w2p[2] + bbp[2];
;                     yv[3] = __builtin_shufflevector(uph, uph, 6, 7) * w0p[3] + __builtin_shufflevector(ggh, ggh, 6, 7) * w1p[3] + __builtin_shufflevector(dnh, dnh, 6, 7) * w2p[3] + bbp[3];
;                     u32x4 o;
; #pragma unroll
;                     for (int n = 0; n < 2; ++n)
; #pragma unroll
;                         for (int q = 0; q < 2; ++q) { const int j = 2 * n + q;
	v_exp_f16_e32 v183, v139
	v_exp_f16_e32 v189, v179
	v_exp_f16_sdwa v183, v139 dst_sel:WORD_1 dst_unused:UNUSED_PRESERVE src0_sel:WORD_1
	v_exp_f16_sdwa v189, v179 dst_sel:WORD_1 dst_unused:UNUSED_PRESERVE src0_sel:WORD_1
	v_pk_mul_f16 v138, v183, v138
	v_pk_mul_f16 v178, v189, v178
	v_pk_max_f16 v136, v136, 0
	v_pk_max_f16 v176, v176, 0
	v_pk_fma_f16 v136, v137, v138, v136 neg_lo:[1,0,0] neg_hi:[1,0,0]
	v_pk_fma_f16 v176, v177, v178, v176 neg_lo:[1,0,0] neg_hi:[1,0,0]
	v_cvt_pk_f16_f32 v139, v112, v113
	v_cvt_pk_f16_f32 v179, v114, v115
	v_pk_mul_f16 v152, v139, v136
	v_pk_mul_f16 v153, v179, v176
	v_add_u32_e32 v152, 0x40004, v152
	v_add_u32_e32 v153, 0x40004, v153
	v_and_b32_e32 v152, 0xfff8fff8, v152
	v_and_b32_e32 v153, 0xfff8fff8, v153
	v_mov_b32_dpp v136, v142 row_ror:1 row_mask:0xf bank_mask:0xf
	v_mov_b32_dpp v176, v143 row_ror:1 row_mask:0xf bank_mask:0xf
	v_mov_b32_dpp v136, v146 row_shr:1 row_mask:0xf bank_mask:0xf
	v_mov_b32_dpp v176, v147 row_shr:1 row_mask:0xf bank_mask:0xf
	v_mov_b32_dpp v137, v150 row_ror:15 row_mask:0xf bank_mask:0xf
	v_mov_b32_dpp v177, v151 row_ror:15 row_mask:0xf bank_mask:0xf
	v_mov_b32_dpp v137, v146 row_shl:1 row_mask:0xf bank_mask:0xf
	v_mov_b32_dpp v177, v147 row_shl:1 row_mask:0xf bank_mask:0xf
	v_pk_fma_f16 v136, v136, v166, v162
	v_pk_fma_f16 v176, v176, v167, v163
	v_pk_fma_f16 v136, v146, v170, v136
	v_pk_fma_f16 v176, v147, v171, v176
	v_pk_fma_f16 v136, v137, v158, v136
	v_pk_fma_f16 v176, v177, v159, v176
	v_and_b32_e32 v137, 0x7fff7fff, v136
	v_and_b32_e32 v177, 0x7fff7fff, v176
	v_pk_fma_f16 v138, v137, s45, 1.0 op_sel_hi:[1,0,0]
	v_pk_fma_f16 v178, v177, s45, 1.0 op_sel_hi:[1,0,0]
	v_rcp_f16_e32 v139, v138
	v_rcp_f16_e32 v179, v178
	v_rcp_f16_sdwa v139, v138 dst_sel:WORD_1 dst_unused:UNUSED_PRESERVE src0_sel:WORD_1
	v_rcp_f16_sdwa v179, v178 dst_sel:WORD_1 dst_unused:UNUSED_PRESERVE src0_sel:WORD_1
	v_pk_fma_f16 v138, v139, s55, v228 op_sel_hi:[1,0,0]
	v_pk_fma_f16 v178, v179, s55, v228 op_sel_hi:[1,0,0]
	v_pk_fma_f16 v138, v139, v138, s65 op_sel_hi:[1,1,0]
	v_pk_fma_f16 v178, v179, v178, s65 op_sel_hi:[1,1,0]
	v_pk_fma_f16 v138, v139, v138, s68 op_sel_hi:[1,1,0]
	v_pk_fma_f16 v178, v179, v178, s68 op_sel_hi:[1,1,0]
	v_pk_fma_f16 v138, v139, v138, s69 op_sel_hi:[1,1,0]
	v_pk_fma_f16 v178, v179, v178, s69 op_sel_hi:[1,1,0]
	v_pk_mul_f16 v138, v139, v138
	v_pk_mul_f16 v178, v179, v178
	v_pk_mul_f16 v139, v136, v136
	v_pk_mul_f16 v179, v176, v176
	v_pk_mul_f16 v139, v139, s72 op_sel_hi:[1,0]
	v_pk_mul_f16 v179, v179, s72 op_sel_hi:[1,0]
	v_exp_f16_e32 v183, v139
	v_exp_f16_e32 v189, v179
	v_exp_f16_sdwa v183, v139 dst_sel:WORD_1 dst_unused:UNUSED_PRESERVE src0_sel:WORD_1
	v_exp_f16_sdwa v189, v179 dst_sel:WORD_1 dst_unused:UNUSED_PRESERVE src0_sel:WORD_1
	v_pk_mul_f16 v138, v183, v138
	v_pk_mul_f16 v178, v189, v178
	v_pk_max_f16 v136, v136, 0
	v_pk_max_f16 v176, v176, 0
	v_pk_fma_f16 v136, v137, v138, v136 neg_lo:[1,0,0] neg_hi:[1,0,0]
	v_pk_fma_f16 v176, v177, v178, v176 neg_lo:[1,0,0] neg_hi:[1,0,0]
	v_cvt_pk_f16_f32 v139, v108, v109
	v_cvt_pk_f16_f32 v179, v110, v111
	v_pk_mul_f16 v154, v139, v136
	v_pk_mul_f16 v155, v179, v176
	v_add_u32_e32 v154, 0x40004, v154
	v_add_u32_e32 v155, 0x40004, v155
	v_and_b32_e32 v154, 0xfff8fff8, v154
	v_and_b32_e32 v155, 0xfff8fff8, v155
	v_add_u32_e32 v194, 16, v32
	v_mad_i64_i32 v[194:195], vcc, v194, s29, v[192:193]
	global_store_dwordx4 v[194:195], v[152:155], off
	v_cvt_pk_f16_f32 v140, v72, v73
	v_cvt_pk_f16_f32 v141, v74, v75
	v_cvt_pk_f16_f32 v142, v68, v69
	v_cvt_pk_f16_f32 v143, v70, v71
	v_mov_b32_dpp v136, v144 row_ror:1 row_mask:0xf bank_mask:0xf
	v_mov_b32_dpp v176, v145 row_ror:1 row_mask:0xf bank_mask:0xf
	v_mov_b32_dpp v136, v148 row_shr:1 row_mask:0xf bank_mask:0xf
	v_mov_b32_dpp v176, v149 row_shr:1 row_mask:0xf bank_mask:0xf
	v_mov_b32_dpp v137, v140 row_ror:15 row_mask:0xf bank_mask:0xf
	v_mov_b32_dpp v177, v141 row_ror:15 row_mask:0xf bank_mask:0xf
	v_mov_b32_dpp v137, v148 row_shl:1 row_mask:0xf bank_mask:0xf
	v_mov_b32_dpp v177, v149 row_shl:1 row_mask:0xf bank_mask:0xf
	v_pk_fma_f16 v136, v136, v164, v160
	v_pk_fma_f16 v176, v176, v165, v161
	v_pk_fma_f16 v136, v148, v168, v136
	v_pk_fma_f16 v176, v149, v169, v176
	v_pk_fma_f16 v136, v137, v156, v136
	v_pk_fma_f16 v176, v177, v157, v176
	v_and_b32_e32 v137, 0x7fff7fff, v136
	v_and_b32_e32 v177, 0x7fff7fff, v176
	v_pk_fma_f16 v138, v137, s45, 1.0 op_sel_hi:[1,0,0]
	v_pk_fma_f16 v178, v177, s45, 1.0 op_sel_hi:[1,0,0]
	v_rcp_f16_e32 v139, v138
	v_rcp_f16_e32 v179, v178
	v_rcp_f16_sdwa v139, v138 dst_sel:WORD_1 dst_unused:UNUSED_PRESERVE src0_sel:WORD_1
	v_rcp_f16_sdwa v179, v178 dst_sel:WORD_1 dst_unused:UNUSED_PRESERVE src0_sel:WORD_1
	v_pk_fma_f16 v138, v139, s55, v228 op_sel_hi:[1,0,0]
	v_pk_fma_f16 v178, v179, s55, v228 op_sel_hi:[1,0,0]
	v_pk_fma_f16 v138, v139, v138, s65 op_sel_hi:[1,1,0]
	v_pk_fma_f16 v178, v179, v178, s65 op_sel_hi:[1,1,0]
	v_pk_fma_f16 v138, v139, v138, s68 op_sel_hi:[1,1,0]
	v_pk_fma_f16 v178, v179, v178, s68 op_sel_hi:[1,1,0]
	v_pk_fma_f16 v138, v139, v138, s69 op_sel_hi:[1,1,0]
	v_pk_fma_f16 v178, v179, v178, s69 op_sel_hi:[1,1,0]
	v_pk_mul_f16 v138, v139, v138
	v_pk_mul_f16 v178, v179, v178
	v_pk_mul_f16 v139, v136, v136
	v_pk_mul_f16 v179, v176, v176
	v_pk_mul_f16 v139, v139, s72 op_sel_hi:[1,0]
	v_pk_mul_f16 v179, v179, s72 op_sel_hi:[1,0]
	v_exp_f16_e32 v183, v139
	v_exp_f16_e32 v189, v179
	v_exp_f16_sdwa v183, v139 dst_sel:WORD_1 dst_unused:UNUSED_PRESERVE src0_sel:WORD_1
	v_exp_f16_sdwa v189, v179 dst_sel:WORD_1 dst_unused:UNUSED_PRESERVE src0_sel:WORD_1
	v_pk_mul_f16 v138, v183, v138
	v_pk_mul_f16 v178, v189, v178
	v_pk_max_f16 v136, v136, 0
; __device__ __forceinline__ int shl_(int v, int src_lane) { return __builtin_amdgcn_ds_bpermute(src_lane << 2, v); }
;     __device__ __forceinline__ void operator()(const f32x4 (&acc)[2][2][4][2], const GUnit& u, int wr, int wc, int fr, int fq, LAS unsigned char* lds) const {
;     ...
;                 for (int m = 0; m < 4; ++m) {
;                     u32x4 UP, DN, GG;
; #pragma unroll
;                     for (int j = 0; j < 4; ++j) { const int g = (int)gp[m][j];
;                         const int oldu = m > 0 ? shl_((int)gp[m > 0 ? m - 1 : 0][j], lane15) : (int)eup[j];
;                         const int ups = __builtin_amdgcn_update_dpp(0, g, 0x111, 0xf, 0xf, true);
;                         const int oldd = m < 3 ? shl_((int)gp[m < 3 ? m + 1 : 3][j], lane0r) : (int)edp[j];
;                         const int dns = __builtin_amdgcn_update_dpp(0, g, 0x101, 0xf, 0xf, true);
;                         UP[j] = (unsigned)(frL == 0 ? oldu : ups); DN[j] = (unsigned)(frL == 15 ? oldd : dns); GG[j] = (unsigned)g; }
;                     const f16x8 uph = __builtin_bit_cast(f16x8, UP), dnh = __builtin_bit_cast(f16x8, DN), ggh = __builtin_bit_cast(f16x8, GG);
;                     f16x2 yv[4];
;                     yv[0] = __builtin_shufflevector(uph, uph, 0, 1) * w0p[0] + __builtin_shufflevector(ggh, ggh, 0, 1) * w1p[0] + __builtin_shufflevector(dnh, dnh, 0, 1) * w2p[0] + bbp[0];
;                     yv[1] = __builtin_shufflevector(uph, uph, 2, 3) * w0p[1] + __builtin_shufflevector(ggh, ggh, 2, 3) * w1p[1] + __builtin_shufflevector(dnh, dnh, 2, 3) * w2p[1] + bbp[1];
;                     yv[2] = __builtin_shufflevector(uph, uph, 4, 5) * w0p[2] + __builtin_shufflevector(ggh, ggh, 4, 5) * w1p[2] + __builtin_shufflevector(dnh, dnh, 4, 5) * w2p[2] + bbp[2];
;                     yv[3] = __builtin_shufflevector(uph, uph, 6, 7) * w0p[3] + __builtin_shufflevector(ggh, ggh, 6, 7) * w1p[3] + __builtin_shufflevector(dnh, dnh, 6, 7) * w2p[3] + bbp[3];
;                     u32x4 o;
; #pragma unroll
;                     for (int n = 0; n < 2; ++n)
; #pragma unroll
;                         for (int q = 0; q < 2; ++q) { const int j = 2 * n + q;
	v_pk_max_f16 v176, v176, 0
	v_pk_fma_f16 v136, v137, v138, v136 neg_lo:[1,0,0] neg_hi:[1,0,0]
	v_pk_fma_f16 v176, v177, v178, v176 neg_lo:[1,0,0] neg_hi:[1,0,0]
	v_cvt_pk_f16_f32 v139, v96, v97
	v_cvt_pk_f16_f32 v179, v98, v99
	v_pk_mul_f16 v152, v139, v136
	v_pk_mul_f16 v153, v179, v176
	v_add_u32_e32 v152, 0x40004, v152
	v_add_u32_e32 v153, 0x40004, v153
	v_and_b32_e32 v152, 0xfff8fff8, v152
	v_and_b32_e32 v153, 0xfff8fff8, v153
	v_mov_b32_dpp v136, v146 row_ror:1 row_mask:0xf bank_mask:0xf
	v_mov_b32_dpp v176, v147 row_ror:1 row_mask:0xf bank_mask:0xf
	v_mov_b32_dpp v136, v150 row_shr:1 row_mask:0xf bank_mask:0xf
	v_mov_b32_dpp v176, v151 row_shr:1 row_mask:0xf bank_mask:0xf
	v_mov_b32_dpp v137, v142 row_ror:15 row_mask:0xf bank_mask:0xf
	v_mov_b32_dpp v177, v143 row_ror:15 row_mask:0xf bank_mask:0xf
	v_mov_b32_dpp v137, v150 row_shl:1 row_mask:0xf bank_mask:0xf
	v_mov_b32_dpp v177, v151 row_shl:1 row_mask:0xf bank_mask:0xf
	v_pk_fma_f16 v136, v136, v166, v162
	v_pk_fma_f16 v176, v176, v167, v163
	v_pk_fma_f16 v136, v150, v170, v136
	v_pk_fma_f16 v176, v151, v171, v176
	v_pk_fma_f16 v136, v137, v158, v136
	v_pk_fma_f16 v176, v177, v159, v176
	v_and_b32_e32 v137, 0x7fff7fff, v136
	v_and_b32_e32 v177, 0x7fff7fff, v176
	v_pk_fma_f16 v138, v137, s45, 1.0 op_sel_hi:[1,0,0]
	v_pk_fma_f16 v178, v177, s45, 1.0 op_sel_hi:[1,0,0]
	v_rcp_f16_e32 v139, v138
	v_rcp_f16_e32 v179, v178
	v_rcp_f16_sdwa v139, v138 dst_sel:WORD_1 dst_unused:UNUSED_PRESERVE src0_sel:WORD_1
	v_rcp_f16_sdwa v179, v178 dst_sel:WORD_1 dst_unused:UNUSED_PRESERVE src0_sel:WORD_1
	v_pk_fma_f16 v138, v139, s55, v228 op_sel_hi:[1,0,0]
	v_pk_fma_f16 v178, v179, s55, v228 op_sel_hi:[1,0,0]
	v_pk_fma_f16 v138, v139, v138, s65 op_sel_hi:[1,1,0]
	v_pk_fma_f16 v178, v179, v178, s65 op_sel_hi:[1,1,0]
	v_pk_fma_f16 v138, v139, v138, s68 op_sel_hi:[1,1,0]
	v_pk_fma_f16 v178, v179, v178, s68 op_sel_hi:[1,1,0]
	v_pk_fma_f16 v138, v139, v138, s69 op_sel_hi:[1,1,0]
	v_pk_fma_f16 v178, v179, v178, s69 op_sel_hi:[1,1,0]
	v_pk_mul_f16 v138, v139, v138
	v_pk_mul_f16 v178, v179, v178
	v_pk_mul_f16 v139, v136, v136
	v_pk_mul_f16 v179, v176, v176
	v_pk_mul_f16 v139, v139, s72 op_sel_hi:[1,0]
	v_pk_mul_f16 v179, v179, s72 op_sel_hi:[1,0]
	v_exp_f16_e32 v183, v139
	v_exp_f16_e32 v189, v179
	v_exp_f16_sdwa v183, v139 dst_sel:WORD_1 dst_unused:UNUSED_PRESERVE src0_sel:WORD_1
	v_exp_f16_sdwa v189, v179 dst_sel:WORD_1 dst_unused:UNUSED_PRESERVE src0_sel:WORD_1
	v_pk_mul_f16 v138, v183, v138
	v_pk_mul_f16 v178, v189, v178
	v_pk_max_f16 v136, v136, 0
	v_pk_max_f16 v176, v176, 0
	v_pk_fma_f16 v136, v137, v138, v136 neg_lo:[1,0,0] neg_hi:[1,0,0]
	v_pk_fma_f16 v176, v177, v178, v176 neg_lo:[1,0,0] neg_hi:[1,0,0]
	v_cvt_pk_f16_f32 v139, v92, v93
	v_cvt_pk_f16_f32 v179, v94, v95
	v_pk_mul_f16 v154, v139, v136
	v_pk_mul_f16 v155, v179, v176
	v_add_u32_e32 v154, 0x40004, v154
	v_add_u32_e32 v155, 0x40004, v155
	v_and_b32_e32 v154, 0xfff8fff8, v154
	v_and_b32_e32 v155, 0xfff8fff8, v155
	v_add_u32_e32 v194, 32, v32
	v_mad_i64_i32 v[194:195], vcc, v194, s29, v[192:193]
	global_store_dwordx4 v[194:195], v[152:155], off
	v_mov_b32_dpp v136, v148 row_ror:1 row_mask:0xf bank_mask:0xf
	v_mov_b32_dpp v176, v149 row_ror:1 row_mask:0xf bank_mask:0xf
	v_mov_b32_dpp v136, v140 row_shr:1 row_mask:0xf bank_mask:0xf
	v_mov_b32_dpp v176, v141 row_shr:1 row_mask:0xf bank_mask:0xf
	v_mov_b32_dpp v132, v140 row_shl:1 row_mask:0xf bank_mask:0xf
	v_mov_b32_dpp v133, v141 row_shl:1 row_mask:0xf bank_mask:0xf
	v_pk_fma_f16 v136, v136, v164, v160
	v_pk_fma_f16 v176, v176, v165, v161
	v_pk_fma_f16 v136, v140, v168, v136
	v_pk_fma_f16 v176, v141, v169, v176
	v_pk_fma_f16 v136, v132, v156, v136
	v_pk_fma_f16 v176, v133, v157, v176
	v_and_b32_e32 v137, 0x7fff7fff, v136
	v_and_b32_e32 v177, 0x7fff7fff, v176
	v_pk_fma_f16 v138, v137, s45, 1.0 op_sel_hi:[1,0,0]
	v_pk_fma_f16 v178, v177, s45, 1.0 op_sel_hi:[1,0,0]
	v_rcp_f16_e32 v139, v138
	v_rcp_f16_e32 v179, v178
	v_rcp_f16_sdwa v139, v138 dst_sel:WORD_1 dst_unused:UNUSED_PRESERVE src0_sel:WORD_1
	v_rcp_f16_sdwa v179, v178 dst_sel:WORD_1 dst_unused:UNUSED_PRESERVE src0_sel:WORD_1
	v_pk_fma_f16 v138, v139, s55, v228 op_sel_hi:[1,0,0]
	v_pk_fma_f16 v178, v179, s55, v228 op_sel_hi:[1,0,0]
	v_pk_fma_f16 v138, v139, v138, s65 op_sel_hi:[1,1,0]
	v_pk_fma_f16 v178, v179, v178, s65 op_sel_hi:[1,1,0]
	v_pk_fma_f16 v138, v139, v138, s68 op_sel_hi:[1,1,0]
	v_pk_fma_f16 v178, v179, v178, s68 op_sel_hi:[1,1,0]
	v_pk_fma_f16 v138, v139, v138, s69 op_sel_hi:[1,1,0]
	v_pk_fma_f16 v178, v179, v178, s69 op_sel_hi:[1,1,0]
	v_pk_mul_f16 v138, v139, v138
	v_pk_mul_f16 v178, v179, v178
	v_pk_mul_f16 v139, v136, v136
	v_pk_mul_f16 v179, v176, v176
	v_pk_mul_f16 v139, v139, s72 op_sel_hi:[1,0]
	v_pk_mul_f16 v179, v179, s72 op_sel_hi:[1,0]
	v_exp_f16_e32 v183, v139
	v_exp_f16_e32 v189, v179
	v_exp_f16_sdwa v183, v139 dst_sel:WORD_1 dst_unused:UNUSED_PRESERVE src0_sel:WORD_1
	v_exp_f16_sdwa v189, v179 dst_sel:WORD_1 dst_unused:UNUSED_PRESERVE src0_sel:WORD_1
	v_pk_mul_f16 v138, v183, v138
	v_pk_mul_f16 v178, v189, v178
	v_pk_max_f16 v136, v136, 0
	v_pk_max_f16 v176, v176, 0
	v_pk_fma_f16 v136, v137, v138, v136 neg_lo:[1,0,0] neg_hi:[1,0,0]
	v_pk_fma_f16 v176, v177, v178, v176 neg_lo:[1,0,0] neg_hi:[1,0,0]
	v_cvt_pk_f16_f32 v139, v80, v81
	v_cvt_pk_f16_f32 v179, v82, v83
	v_pk_mul_f16 v152, v139, v136
	v_pk_mul_f16 v153, v179, v176
	v_add_u32_e32 v152, 0x40004, v152
	v_add_u32_e32 v153, 0x40004, v153
	v_and_b32_e32 v152, 0xfff8fff8, v152
	v_and_b32_e32 v153, 0xfff8fff8, v153
	v_mov_b32_dpp v136, v150 row_ror:1 row_mask:0xf bank_mask:0xf
	v_mov_b32_dpp v176, v151 row_ror:1 row_mask:0xf bank_mask:0xf
; __device__ __forceinline__ int shl_(int v, int src_lane) { return __builtin_amdgcn_ds_bpermute(src_lane << 2, v); }
;     __device__ __forceinline__ void operator()(const f32x4 (&acc)[2][2][4][2], const GUnit& u, int wr, int wc, int fr, int fq, LAS unsigned char* lds) const {
;     ...
;                 for (int m = 0; m < 4; ++m) {
;                     u32x4 UP, DN, GG;
; #pragma unroll
;                     for (int j = 0; j < 4; ++j) { const int g = (int)gp[m][j];
;                         const int oldu = m > 0 ? shl_((int)gp[m > 0 ? m - 1 : 0][j], lane15) : (int)eup[j];
;                         const int ups = __builtin_amdgcn_update_dpp(0, g, 0x111, 0xf, 0xf, true);
;                         const int oldd = m < 3 ? shl_((int)gp[m < 3 ? m + 1 : 3][j], lane0r) : (int)edp[j];
;                         const int dns = __builtin_amdgcn_update_dpp(0, g, 0x101, 0xf, 0xf, true);
;                         UP[j] = (unsigned)(frL == 0 ? oldu : ups); DN[j] = (unsigned)(frL == 15 ? oldd : dns); GG[j] = (unsigned)g; }
;                     const f16x8 uph = __builtin_bit_cast(f16x8, UP), dnh = __builtin_bit_cast(f16x8, DN), ggh = __builtin_bit_cast(f16x8, GG);
;                     f16x2 yv[4];
;                     yv[0] = __builtin_shufflevector(uph, uph, 0, 1) * w0p[0] + __builtin_shufflevector(ggh, ggh, 0, 1) * w1p[0] + __builtin_shufflevector(dnh, dnh, 0, 1) * w2p[0] + bbp[0];
;                     yv[1] = __builtin_shufflevector(uph, uph, 2, 3) * w0p[1] + __builtin_shufflevector(ggh, ggh, 2, 3) * w1p[1] + __builtin_shufflevector(dnh, dnh, 2, 3) * w2p[1] + bbp[1];
;                     yv[2] = __builtin_shufflevector(uph, uph, 4, 5) * w0p[2] + __builtin_shufflevector(ggh, ggh, 4, 5) * w1p[2] + __builtin_shufflevector(dnh, dnh, 4, 5) * w2p[2] + bbp[2];
;                     yv[3] = __builtin_shufflevector(uph, uph, 6, 7) * w0p[3] + __builtin_shufflevector(ggh, ggh, 6, 7) * w1p[3] + __builtin_shufflevector(dnh, dnh, 6, 7) * w2p[3] + bbp[3];
;                     u32x4 o;
; #pragma unroll
;                     for (int n = 0; n < 2; ++n)
; #pragma unroll
;                         for (int q = 0; q < 2; ++q) { const int j = 2 * n + q;
	v_mov_b32_dpp v136, v142 row_shr:1 row_mask:0xf bank_mask:0xf
	v_mov_b32_dpp v176, v143 row_shr:1 row_mask:0xf bank_mask:0xf
	v_mov_b32_dpp v134, v142 row_shl:1 row_mask:0xf bank_mask:0xf
	v_mov_b32_dpp v135, v143 row_shl:1 row_mask:0xf bank_mask:0xf
	v_pk_fma_f16 v136, v136, v166, v162
	v_pk_fma_f16 v176, v176, v167, v163
	v_pk_fma_f16 v136, v142, v170, v136
	v_pk_fma_f16 v176, v143, v171, v176
	v_pk_fma_f16 v136, v134, v158, v136
	v_pk_fma_f16 v176, v135, v159, v176
	v_and_b32_e32 v137, 0x7fff7fff, v136
	v_and_b32_e32 v177, 0x7fff7fff, v176
	v_pk_fma_f16 v138, v137, s45, 1.0 op_sel_hi:[1,0,0]
	v_pk_fma_f16 v178, v177, s45, 1.0 op_sel_hi:[1,0,0]
	v_rcp_f16_e32 v139, v138
	v_rcp_f16_e32 v179, v178
	v_rcp_f16_sdwa v139, v138 dst_sel:WORD_1 dst_unused:UNUSED_PRESERVE src0_sel:WORD_1
	v_rcp_f16_sdwa v179, v178 dst_sel:WORD_1 dst_unused:UNUSED_PRESERVE src0_sel:WORD_1
	v_pk_fma_f16 v138, v139, s55, v228 op_sel_hi:[1,0,0]
	v_pk_fma_f16 v178, v179, s55, v228 op_sel_hi:[1,0,0]
	v_pk_fma_f16 v138, v139, v138, s65 op_sel_hi:[1,1,0]
	v_pk_fma_f16 v178, v179, v178, s65 op_sel_hi:[1,1,0]
	v_pk_fma_f16 v138, v139, v138, s68 op_sel_hi:[1,1,0]
	v_pk_fma_f16 v178, v179, v178, s68 op_sel_hi:[1,1,0]
	v_pk_fma_f16 v138, v139, v138, s69 op_sel_hi:[1,1,0]
	v_pk_fma_f16 v178, v179, v178, s69 op_sel_hi:[1,1,0]
	v_pk_mul_f16 v138, v139, v138
	v_pk_mul_f16 v178, v179, v178
	v_pk_mul_f16 v139, v136, v136
	v_pk_mul_f16 v179, v176, v176
	v_pk_mul_f16 v139, v139, s72 op_sel_hi:[1,0]
	v_pk_mul_f16 v179, v179, s72 op_sel_hi:[1,0]
	v_exp_f16_e32 v183, v139
	v_exp_f16_e32 v189, v179
	v_exp_f16_sdwa v183, v139 dst_sel:WORD_1 dst_unused:UNUSED_PRESERVE src0_sel:WORD_1
	v_exp_f16_sdwa v189, v179 dst_sel:WORD_1 dst_unused:UNUSED_PRESERVE src0_sel:WORD_1
	v_pk_mul_f16 v138, v183, v138
	v_pk_mul_f16 v178, v189, v178
	v_pk_max_f16 v136, v136, 0
	v_pk_max_f16 v176, v176, 0
	v_pk_fma_f16 v136, v137, v138, v136 neg_lo:[1,0,0] neg_hi:[1,0,0]
	v_pk_fma_f16 v176, v177, v178, v176 neg_lo:[1,0,0] neg_hi:[1,0,0]
	v_cvt_pk_f16_f32 v139, v76, v77
	v_cvt_pk_f16_f32 v179, v78, v79
	v_pk_mul_f16 v154, v139, v136
	v_pk_mul_f16 v155, v179, v176
	v_add_u32_e32 v154, 0x40004, v154
	v_add_u32_e32 v155, 0x40004, v155
	v_and_b32_e32 v154, 0xfff8fff8, v154
	v_and_b32_e32 v155, 0xfff8fff8, v155
	v_add_u32_e32 v194, 48, v32
	v_mad_i64_i32 v[194:195], vcc, v194, s29, v[192:193]
	global_store_dwordx4 v[194:195], v[152:155], off
	v_lshlrev_b32_e32 v183, 2, v181
	v_readlane_b32 s12, v251, 60
	v_readlane_b32 s13, v251, 59
	s_nop 1
	v_add_u32_e32 v189, s12, v183
	v_add_u32_e32 v183, s13, v183
	ds_read_b128 v[176:179], v189
	ds_read_b128 v[140:143], v189 offset:16
	s_cmp_eq_u32 s48, 0
	s_cbranch_scc0 .Lffn_no_ed
	ds_read_b128 v[136:139], v183 offset:1024
	ds_read_b128 v[144:147], v183 offset:1040
	s_branch .Lffn_ed_done
.Lffn_no_ed:
	v_mov_b32_e32 v136, 0
	v_mov_b32_e32 v137, 0
	v_mov_b32_e32 v138, 0
	v_mov_b32_e32 v139, 0
	v_mov_b32_e32 v144, 0
	v_mov_b32_e32 v145, 0
	v_mov_b32_e32 v146, 0
	v_mov_b32_e32 v147, 0
.Lffn_ed_done:
	s_waitcnt lgkmcnt(0)
	v_cvt_pk_f16_f32 v172, v176, v177
	v_cvt_pk_f16_f32 v173, v178, v179
	v_cvt_pk_f16_f32 v174, v140, v141
	v_cvt_pk_f16_f32 v175, v142, v143
	v_cvt_pk_f16_f32 v132, v136, v137
	v_cvt_pk_f16_f32 v133, v138, v139
	v_cvt_pk_f16_f32 v134, v144, v145
	v_cvt_pk_f16_f32 v135, v146, v147
	v_cvt_pk_f16_f32 v140, v56, v57
	v_cvt_pk_f16_f32 v141, v58, v59
	v_cvt_pk_f16_f32 v142, v52, v53
	v_cvt_pk_f16_f32 v143, v54, v55
	v_cvt_pk_f16_f32 v144, v40, v41
	v_cvt_pk_f16_f32 v145, v42, v43
	v_cvt_pk_f16_f32 v146, v36, v37
	v_cvt_pk_f16_f32 v147, v38, v39
	v_mov_b32_dpp v172, v140 row_shr:1 row_mask:0xf bank_mask:0xf
	v_mov_b32_dpp v173, v141 row_shr:1 row_mask:0xf bank_mask:0xf
	v_mov_b32_dpp v137, v144 row_ror:15 row_mask:0xf bank_mask:0xf
	v_mov_b32_dpp v177, v145 row_ror:15 row_mask:0xf bank_mask:0xf
	v_mov_b32_dpp v137, v140 row_shl:1 row_mask:0xf bank_mask:0xf
	v_mov_b32_dpp v177, v141 row_shl:1 row_mask:0xf bank_mask:0xf
	v_pk_fma_f16 v136, v172, v164, v160
	v_pk_fma_f16 v176, v173, v165, v161
	v_pk_fma_f16 v136, v140, v168, v136
	v_pk_fma_f16 v176, v141, v169, v176
	v_pk_fma_f16 v136, v137, v156, v136
	v_pk_fma_f16 v176, v177, v157, v176
	v_and_b32_e32 v137, 0x7fff7fff, v136
	v_and_b32_e32 v177, 0x7fff7fff, v176
	v_pk_fma_f16 v138, v137, s45, 1.0 op_sel_hi:[1,0,0]
	v_pk_fma_f16 v178, v177, s45, 1.0 op_sel_hi:[1,0,0]
	v_rcp_f16_e32 v139, v138
	v_rcp_f16_e32 v179, v178
	v_rcp_f16_sdwa v139, v138 dst_sel:WORD_1 dst_unused:UNUSED_PRESERVE src0_sel:WORD_1
	v_rcp_f16_sdwa v179, v178 dst_sel:WORD_1 dst_unused:UNUSED_PRESERVE src0_sel:WORD_1
	v_pk_fma_f16 v138, v139, s55, v228 op_sel_hi:[1,0,0]
	v_pk_fma_f16 v178, v179, s55, v228 op_sel_hi:[1,0,0]
	v_pk_fma_f16 v138, v139, v138, s65 op_sel_hi:[1,1,0]
	v_pk_fma_f16 v178, v179, v178, s65 op_sel_hi:[1,1,0]
	v_pk_fma_f16 v138, v139, v138, s68 op_sel_hi:[1,1,0]
	v_pk_fma_f16 v178, v179, v178, s68 op_sel_hi:[1,1,0]
	v_pk_fma_f16 v138, v139, v138, s69 op_sel_hi:[1,1,0]
	v_pk_fma_f16 v178, v179, v178, s69 op_sel_hi:[1,1,0]
	v_pk_mul_f16 v138, v139, v138
	v_pk_mul_f16 v178, v179, v178
	v_pk_mul_f16 v139, v136, v136
	v_pk_mul_f16 v179, v176, v176
	v_pk_mul_f16 v139, v139, s72 op_sel_hi:[1,0]
	v_pk_mul_f16 v179, v179, s72 op_sel_hi:[1,0]
	v_exp_f16_e32 v183, v139
	v_exp_f16_e32 v189, v179
	v_exp_f16_sdwa v183, v139 dst_sel:WORD_1 dst_unused:UNUSED_PRESERVE src0_sel:WORD_1
	v_exp_f16_sdwa v189, v179 dst_sel:WORD_1 dst_unused:UNUSED_PRESERVE src0_sel:WORD_1
	v_pk_mul_f16 v138, v183, v138
	v_pk_mul_f16 v178, v189, v178
	v_pk_max_f16 v136, v136, 0
	v_pk_max_f16 v176, v176, 0
	v_pk_fma_f16 v136, v137, v138, v136 neg_lo:[1,0,0] neg_hi:[1,0,0]
; __device__ __forceinline__ int shl_(int v, int src_lane) { return __builtin_amdgcn_ds_bpermute(src_lane << 2, v); }
;     __device__ __forceinline__ void operator()(const f32x4 (&acc)[2][2][4][2], const GUnit& u, int wr, int wc, int fr, int fq, LAS unsigned char* lds) const {
;     ...
;                 for (int m = 0; m < 4; ++m) {
;                     u32x4 UP, DN, GG;
; #pragma unroll
;                     for (int j = 0; j < 4; ++j) { const int g = (int)gp[m][j];
;                         const int oldu = m > 0 ? shl_((int)gp[m > 0 ? m - 1 : 0][j], lane15) : (int)eup[j];
;                         const int ups = __builtin_amdgcn_update_dpp(0, g, 0x111, 0xf, 0xf, true);
;                         const int oldd = m < 3 ? shl_((int)gp[m < 3 ? m + 1 : 3][j], lane0r) : (int)edp[j];
;                         const int dns = __builtin_amdgcn_update_dpp(0, g, 0x101, 0xf, 0xf, true);
;                         UP[j] = (unsigned)(frL == 0 ? oldu : ups); DN[j] = (unsigned)(frL == 15 ? oldd : dns); GG[j] = (unsigned)g; }
;                     const f16x8 uph = __builtin_bit_cast(f16x8, UP), dnh = __builtin_bit_cast(f16x8, DN), ggh = __builtin_bit_cast(f16x8, GG);
;                     f16x2 yv[4];
;                     yv[0] = __builtin_shufflevector(uph, uph, 0, 1) * w0p[0] + __builtin_shufflevector(ggh, ggh, 0, 1) * w1p[0] + __builtin_shufflevector(dnh, dnh, 0, 1) * w2p[0] + bbp[0];
;                     yv[1] = __builtin_shufflevector(uph, uph, 2, 3) * w0p[1] + __builtin_shufflevector(ggh, ggh, 2, 3) * w1p[1] + __builtin_shufflevector(dnh, dnh, 2, 3) * w2p[1] + bbp[1];
;                     yv[2] = __builtin_shufflevector(uph, uph, 4, 5) * w0p[2] + __builtin_shufflevector(ggh, ggh, 4, 5) * w1p[2] + __builtin_shufflevector(dnh, dnh, 4, 5) * w2p[2] + bbp[2];
;                     yv[3] = __builtin_shufflevector(uph, uph, 6, 7) * w0p[3] + __builtin_shufflevector(ggh, ggh, 6, 7) * w1p[3] + __builtin_shufflevector(dnh, dnh, 6, 7) * w2p[3] + bbp[3];
;                     u32x4 o;
; #pragma unroll
;                     for (int n = 0; n < 2; ++n)
; #pragma unroll
;                         for (int q = 0; q < 2; ++q) { const int j = 2 * n + q;
	v_pk_fma_f16 v176, v177, v178, v176 neg_lo:[1,0,0] neg_hi:[1,0,0]
	v_cvt_pk_f16_f32 v139, v64, v65
	v_cvt_pk_f16_f32 v179, v66, v67
	v_pk_mul_f16 v152, v139, v136
	v_pk_mul_f16 v153, v179, v176
	v_add_u32_e32 v152, 0x40004, v152
	v_add_u32_e32 v153, 0x40004, v153
	v_and_b32_e32 v152, 0xfff8fff8, v152
	v_and_b32_e32 v153, 0xfff8fff8, v153
	v_mov_b32_dpp v174, v142 row_shr:1 row_mask:0xf bank_mask:0xf
	v_mov_b32_dpp v175, v143 row_shr:1 row_mask:0xf bank_mask:0xf
	v_mov_b32_dpp v137, v146 row_ror:15 row_mask:0xf bank_mask:0xf
	v_mov_b32_dpp v177, v147 row_ror:15 row_mask:0xf bank_mask:0xf
	v_mov_b32_dpp v137, v142 row_shl:1 row_mask:0xf bank_mask:0xf
	v_mov_b32_dpp v177, v143 row_shl:1 row_mask:0xf bank_mask:0xf
	v_pk_fma_f16 v136, v174, v166, v162
	v_pk_fma_f16 v176, v175, v167, v163
	v_pk_fma_f16 v136, v142, v170, v136
	v_pk_fma_f16 v176, v143, v171, v176
	v_pk_fma_f16 v136, v137, v158, v136
	v_pk_fma_f16 v176, v177, v159, v176
	v_and_b32_e32 v137, 0x7fff7fff, v136
	v_and_b32_e32 v177, 0x7fff7fff, v176
	v_pk_fma_f16 v138, v137, s45, 1.0 op_sel_hi:[1,0,0]
	v_pk_fma_f16 v178, v177, s45, 1.0 op_sel_hi:[1,0,0]
	v_rcp_f16_e32 v139, v138
	v_rcp_f16_e32 v179, v178
	v_rcp_f16_sdwa v139, v138 dst_sel:WORD_1 dst_unused:UNUSED_PRESERVE src0_sel:WORD_1
	v_rcp_f16_sdwa v179, v178 dst_sel:WORD_1 dst_unused:UNUSED_PRESERVE src0_sel:WORD_1
	v_pk_fma_f16 v138, v139, s55, v228 op_sel_hi:[1,0,0]
	v_pk_fma_f16 v178, v179, s55, v228 op_sel_hi:[1,0,0]
	v_pk_fma_f16 v138, v139, v138, s65 op_sel_hi:[1,1,0]
	v_pk_fma_f16 v178, v179, v178, s65 op_sel_hi:[1,1,0]
	v_pk_fma_f16 v138, v139, v138, s68 op_sel_hi:[1,1,0]
	v_pk_fma_f16 v178, v179, v178, s68 op_sel_hi:[1,1,0]
	v_pk_fma_f16 v138, v139, v138, s69 op_sel_hi:[1,1,0]
	v_pk_fma_f16 v178, v179, v178, s69 op_sel_hi:[1,1,0]
	v_pk_mul_f16 v138, v139, v138
	v_pk_mul_f16 v178, v179, v178
	v_pk_mul_f16 v139, v136, v136
	v_pk_mul_f16 v179, v176, v176
	v_pk_mul_f16 v139, v139, s72 op_sel_hi:[1,0]
	v_pk_mul_f16 v179, v179, s72 op_sel_hi:[1,0]
	v_exp_f16_e32 v183, v139
	v_exp_f16_e32 v189, v179
	v_exp_f16_sdwa v183, v139 dst_sel:WORD_1 dst_unused:UNUSED_PRESERVE src0_sel:WORD_1
	v_exp_f16_sdwa v189, v179 dst_sel:WORD_1 dst_unused:UNUSED_PRESERVE src0_sel:WORD_1
	v_pk_mul_f16 v138, v183, v138
	v_pk_mul_f16 v178, v189, v178
	v_pk_max_f16 v136, v136, 0
	v_pk_max_f16 v176, v176, 0
	v_pk_fma_f16 v136, v137, v138, v136 neg_lo:[1,0,0] neg_hi:[1,0,0]
	v_pk_fma_f16 v176, v177, v178, v176 neg_lo:[1,0,0] neg_hi:[1,0,0]
	v_cvt_pk_f16_f32 v139, v60, v61
	v_cvt_pk_f16_f32 v179, v62, v63
	v_pk_mul_f16 v154, v139, v136
	v_pk_mul_f16 v155, v179, v176
	v_add_u32_e32 v154, 0x40004, v154
	v_add_u32_e32 v155, 0x40004, v155
	v_and_b32_e32 v154, 0xfff8fff8, v154
	v_and_b32_e32 v155, 0xfff8fff8, v155
	v_add_u32_e32 v194, 0x80, v32
	v_mad_i64_i32 v[194:195], vcc, v194, s29, v[192:193]
	global_store_dwordx4 v[194:195], v[152:155], off
	v_cvt_pk_f16_f32 v148, v20, v21
	v_cvt_pk_f16_f32 v149, v22, v23
	v_cvt_pk_f16_f32 v150, v16, v17
	v_cvt_pk_f16_f32 v151, v18, v19
	v_mov_b32_dpp v136, v140 row_ror:1 row_mask:0xf bank_mask:0xf
	v_mov_b32_dpp v176, v141 row_ror:1 row_mask:0xf bank_mask:0xf
	v_mov_b32_dpp v136, v144 row_shr:1 row_mask:0xf bank_mask:0xf
	v_mov_b32_dpp v176, v145 row_shr:1 row_mask:0xf bank_mask:0xf
	v_mov_b32_dpp v137, v148 row_ror:15 row_mask:0xf bank_mask:0xf
	v_mov_b32_dpp v177, v149 row_ror:15 row_mask:0xf bank_mask:0xf
	v_mov_b32_dpp v137, v144 row_shl:1 row_mask:0xf bank_mask:0xf
	v_mov_b32_dpp v177, v145 row_shl:1 row_mask:0xf bank_mask:0xf
	v_pk_fma_f16 v136, v136, v164, v160
	v_pk_fma_f16 v176, v176, v165, v161
	v_pk_fma_f16 v136, v144, v168, v136
	v_pk_fma_f16 v176, v145, v169, v176
	v_pk_fma_f16 v136, v137, v156, v136
	v_pk_fma_f16 v176, v177, v157, v176
	v_and_b32_e32 v137, 0x7fff7fff, v136
	v_and_b32_e32 v177, 0x7fff7fff, v176
	v_pk_fma_f16 v138, v137, s45, 1.0 op_sel_hi:[1,0,0]
	v_pk_fma_f16 v178, v177, s45, 1.0 op_sel_hi:[1,0,0]
	v_rcp_f16_e32 v139, v138
	v_rcp_f16_e32 v179, v178
	v_rcp_f16_sdwa v139, v138 dst_sel:WORD_1 dst_unused:UNUSED_PRESERVE src0_sel:WORD_1
	v_rcp_f16_sdwa v179, v178 dst_sel:WORD_1 dst_unused:UNUSED_PRESERVE src0_sel:WORD_1
	v_pk_fma_f16 v138, v139, s55, v228 op_sel_hi:[1,0,0]
	v_pk_fma_f16 v178, v179, s55, v228 op_sel_hi:[1,0,0]
	v_pk_fma_f16 v138, v139, v138, s65 op_sel_hi:[1,1,0]
	v_pk_fma_f16 v178, v179, v178, s65 op_sel_hi:[1,1,0]
	v_pk_fma_f16 v138, v139, v138, s68 op_sel_hi:[1,1,0]
	v_pk_fma_f16 v178, v179, v178, s68 op_sel_hi:[1,1,0]
	v_pk_fma_f16 v138, v139, v138, s69 op_sel_hi:[1,1,0]
	v_pk_fma_f16 v178, v179, v178, s69 op_sel_hi:[1,1,0]
	v_pk_mul_f16 v138, v139, v138
	v_pk_mul_f16 v178, v179, v178
	v_pk_mul_f16 v139, v136, v136
	v_pk_mul_f16 v179, v176, v176
	v_pk_mul_f16 v139, v139, s72 op_sel_hi:[1,0]
	v_pk_mul_f16 v179, v179, s72 op_sel_hi:[1,0]
	v_exp_f16_e32 v183, v139
	v_exp_f16_e32 v189, v179
	v_exp_f16_sdwa v183, v139 dst_sel:WORD_1 dst_unused:UNUSED_PRESERVE src0_sel:WORD_1
	v_exp_f16_sdwa v189, v179 dst_sel:WORD_1 dst_unused:UNUSED_PRESERVE src0_sel:WORD_1
	v_pk_mul_f16 v138, v183, v138
	v_pk_mul_f16 v178, v189, v178
	v_pk_max_f16 v136, v136, 0
	v_pk_max_f16 v176, v176, 0
	v_pk_fma_f16 v136, v137, v138, v136 neg_lo:[1,0,0] neg_hi:[1,0,0]
	v_pk_fma_f16 v176, v177, v178, v176 neg_lo:[1,0,0] neg_hi:[1,0,0]
	v_cvt_pk_f16_f32 v139, v48, v49
	v_cvt_pk_f16_f32 v179, v50, v51
	v_pk_mul_f16 v152, v139, v136
	v_pk_mul_f16 v153, v179, v176
	v_add_u32_e32 v152, 0x40004, v152
	v_add_u32_e32 v153, 0x40004, v153
	v_and_b32_e32 v152, 0xfff8fff8, v152
	v_and_b32_e32 v153, 0xfff8fff8, v153
	v_mov_b32_dpp v136, v142 row_ror:1 row_mask:0xf bank_mask:0xf
	v_mov_b32_dpp v176, v143 row_ror:1 row_mask:0xf bank_mask:0xf
; __device__ __forceinline__ int shl_(int v, int src_lane) { return __builtin_amdgcn_ds_bpermute(src_lane << 2, v); }
;     __device__ __forceinline__ void operator()(const f32x4 (&acc)[2][2][4][2], const GUnit& u, int wr, int wc, int fr, int fq, LAS unsigned char* lds) const {
;     ...
;                 for (int m = 0; m < 4; ++m) {
;                     u32x4 UP, DN, GG;
; #pragma unroll
;                     for (int j = 0; j < 4; ++j) { const int g = (int)gp[m][j];
;                         const int oldu = m > 0 ? shl_((int)gp[m > 0 ? m - 1 : 0][j], lane15) : (int)eup[j];
;                         const int ups = __builtin_amdgcn_update_dpp(0, g, 0x111, 0xf, 0xf, true);
;                         const int oldd = m < 3 ? shl_((int)gp[m < 3 ? m + 1 : 3][j], lane0r) : (int)edp[j];
;                         const int dns = __builtin_amdgcn_update_dpp(0, g, 0x101, 0xf, 0xf, true);
;                         UP[j] = (unsigned)(frL == 0 ? oldu : ups); DN[j] = (unsigned)(frL == 15 ? oldd : dns); GG[j] = (unsigned)g; }
;                     const f16x8 uph = __builtin_bit_cast(f16x8, UP), dnh = __builtin_bit_cast(f16x8, DN), ggh = __builtin_bit_cast(f16x8, GG);
;                     f16x2 yv[4];
;                     yv[0] = __builtin_shufflevector(uph, uph, 0, 1) * w0p[0] + __builtin_shufflevector(ggh, ggh, 0, 1) * w1p[0] + __builtin_shufflevector(dnh, dnh, 0, 1) * w2p[0] + bbp[0];
;                     yv[1] = __builtin_shufflevector(uph, uph, 2, 3) * w0p[1] + __builtin_shufflevector(ggh, ggh, 2, 3) * w1p[1] + __builtin_shufflevector(dnh, dnh, 2, 3) * w2p[1] + bbp[1];
;                     yv[2] = __builtin_shufflevector(uph, uph, 4, 5) * w0p[2] + __builtin_shufflevector(ggh, ggh, 4, 5) * w1p[2] + __builtin_shufflevector(dnh, dnh, 4, 5) * w2p[2] + bbp[2];
;                     yv[3] = __builtin_shufflevector(uph, uph, 6, 7) * w0p[3] + __builtin_shufflevector(ggh, ggh, 6, 7) * w1p[3] + __builtin_shufflevector(dnh, dnh, 6, 7) * w2p[3] + bbp[3];
;                     u32x4 o;
; #pragma unroll
;                     for (int n = 0; n < 2; ++n)
; #pragma unroll
;                         for (int q = 0; q < 2; ++q) { const int j = 2 * n + q;
	v_mov_b32_dpp v136, v146 row_shr:1 row_mask:0xf bank_mask:0xf
	v_mov_b32_dpp v176, v147 row_shr:1 row_mask:0xf bank_mask:0xf
	v_mov_b32_dpp v137, v150 row_ror:15 row_mask:0xf bank_mask:0xf
	v_mov_b32_dpp v177, v151 row_ror:15 row_mask:0xf bank_mask:0xf
	v_mov_b32_dpp v137, v146 row_shl:1 row_mask:0xf bank_mask:0xf
	v_mov_b32_dpp v177, v147 row_shl:1 row_mask:0xf bank_mask:0xf
	v_pk_fma_f16 v136, v136, v166, v162
	v_pk_fma_f16 v176, v176, v167, v163
	v_pk_fma_f16 v136, v146, v170, v136
	v_pk_fma_f16 v176, v147, v171, v176
	v_pk_fma_f16 v136, v137, v158, v136
	v_pk_fma_f16 v176, v177, v159, v176
	v_and_b32_e32 v137, 0x7fff7fff, v136
	v_and_b32_e32 v177, 0x7fff7fff, v176
	v_pk_fma_f16 v138, v137, s45, 1.0 op_sel_hi:[1,0,0]
	v_pk_fma_f16 v178, v177, s45, 1.0 op_sel_hi:[1,0,0]
	v_rcp_f16_e32 v139, v138
	v_rcp_f16_e32 v179, v178
	v_rcp_f16_sdwa v139, v138 dst_sel:WORD_1 dst_unused:UNUSED_PRESERVE src0_sel:WORD_1
	v_rcp_f16_sdwa v179, v178 dst_sel:WORD_1 dst_unused:UNUSED_PRESERVE src0_sel:WORD_1
	v_pk_fma_f16 v138, v139, s55, v228 op_sel_hi:[1,0,0]
	v_pk_fma_f16 v178, v179, s55, v228 op_sel_hi:[1,0,0]
	v_pk_fma_f16 v138, v139, v138, s65 op_sel_hi:[1,1,0]
	v_pk_fma_f16 v178, v179, v178, s65 op_sel_hi:[1,1,0]
	v_pk_fma_f16 v138, v139, v138, s68 op_sel_hi:[1,1,0]
	v_pk_fma_f16 v178, v179, v178, s68 op_sel_hi:[1,1,0]
	v_pk_fma_f16 v138, v139, v138, s69 op_sel_hi:[1,1,0]
	v_pk_fma_f16 v178, v179, v178, s69 op_sel_hi:[1,1,0]
	v_pk_mul_f16 v138, v139, v138
	v_pk_mul_f16 v178, v179, v178
	v_pk_mul_f16 v139, v136, v136
	v_pk_mul_f16 v179, v176, v176
	v_pk_mul_f16 v139, v139, s72 op_sel_hi:[1,0]
	v_pk_mul_f16 v179, v179, s72 op_sel_hi:[1,0]
	v_exp_f16_e32 v183, v139
	v_exp_f16_e32 v189, v179
	v_exp_f16_sdwa v183, v139 dst_sel:WORD_1 dst_unused:UNUSED_PRESERVE src0_sel:WORD_1
	v_exp_f16_sdwa v189, v179 dst_sel:WORD_1 dst_unused:UNUSED_PRESERVE src0_sel:WORD_1
	v_pk_mul_f16 v138, v183, v138
	v_pk_mul_f16 v178, v189, v178
	v_pk_max_f16 v136, v136, 0
	v_pk_max_f16 v176, v176, 0
	v_pk_fma_f16 v136, v137, v138, v136 neg_lo:[1,0,0] neg_hi:[1,0,0]
	v_pk_fma_f16 v176, v177, v178, v176 neg_lo:[1,0,0] neg_hi:[1,0,0]
	v_cvt_pk_f16_f32 v139, v44, v45
	v_cvt_pk_f16_f32 v179, v46, v47
	v_pk_mul_f16 v154, v139, v136
	v_pk_mul_f16 v155, v179, v176
	v_add_u32_e32 v154, 0x40004, v154
	v_add_u32_e32 v155, 0x40004, v155
	v_and_b32_e32 v154, 0xfff8fff8, v154
	v_and_b32_e32 v155, 0xfff8fff8, v155
	v_add_u32_e32 v194, 0x90, v32
	v_mad_i64_i32 v[194:195], vcc, v194, s29, v[192:193]
	global_store_dwordx4 v[194:195], v[152:155], off
	v_cvt_pk_f16_f32 v140, v4, v5
	v_cvt_pk_f16_f32 v141, v6, v7
	v_cvt_pk_f16_f32 v142, v0, v1
	v_cvt_pk_f16_f32 v143, v2, v3
	v_mov_b32_dpp v136, v144 row_ror:1 row_mask:0xf bank_mask:0xf
	v_mov_b32_dpp v176, v145 row_ror:1 row_mask:0xf bank_mask:0xf
	v_mov_b32_dpp v136, v148 row_shr:1 row_mask:0xf bank_mask:0xf
	v_mov_b32_dpp v176, v149 row_shr:1 row_mask:0xf bank_mask:0xf
	v_mov_b32_dpp v137, v140 row_ror:15 row_mask:0xf bank_mask:0xf
	v_mov_b32_dpp v177, v141 row_ror:15 row_mask:0xf bank_mask:0xf
	v_mov_b32_dpp v137, v148 row_shl:1 row_mask:0xf bank_mask:0xf
	v_mov_b32_dpp v177, v149 row_shl:1 row_mask:0xf bank_mask:0xf
	v_pk_fma_f16 v136, v136, v164, v160
	v_pk_fma_f16 v176, v176, v165, v161
	v_pk_fma_f16 v136, v148, v168, v136
	v_pk_fma_f16 v176, v149, v169, v176
	v_pk_fma_f16 v136, v137, v156, v136
	v_pk_fma_f16 v176, v177, v157, v176
	v_and_b32_e32 v137, 0x7fff7fff, v136
	v_and_b32_e32 v177, 0x7fff7fff, v176
	v_pk_fma_f16 v138, v137, s45, 1.0 op_sel_hi:[1,0,0]
	v_pk_fma_f16 v178, v177, s45, 1.0 op_sel_hi:[1,0,0]
	v_rcp_f16_e32 v139, v138
	v_rcp_f16_e32 v179, v178
	v_rcp_f16_sdwa v139, v138 dst_sel:WORD_1 dst_unused:UNUSED_PRESERVE src0_sel:WORD_1
	v_rcp_f16_sdwa v179, v178 dst_sel:WORD_1 dst_unused:UNUSED_PRESERVE src0_sel:WORD_1
	v_pk_fma_f16 v138, v139, s55, v228 op_sel_hi:[1,0,0]
	v_pk_fma_f16 v178, v179, s55, v228 op_sel_hi:[1,0,0]
	v_pk_fma_f16 v138, v139, v138, s65 op_sel_hi:[1,1,0]
	v_pk_fma_f16 v178, v179, v178, s65 op_sel_hi:[1,1,0]
	v_pk_fma_f16 v138, v139, v138, s68 op_sel_hi:[1,1,0]
	v_pk_fma_f16 v178, v179, v178, s68 op_sel_hi:[1,1,0]
	v_pk_fma_f16 v138, v139, v138, s69 op_sel_hi:[1,1,0]
	v_pk_fma_f16 v178, v179, v178, s69 op_sel_hi:[1,1,0]
	v_pk_mul_f16 v138, v139, v138
	v_pk_mul_f16 v178, v179, v178
	v_pk_mul_f16 v139, v136, v136
	v_pk_mul_f16 v179, v176, v176
	v_pk_mul_f16 v139, v139, s72 op_sel_hi:[1,0]
	v_pk_mul_f16 v179, v179, s72 op_sel_hi:[1,0]
	v_exp_f16_e32 v183, v139
	v_exp_f16_e32 v189, v179
	v_exp_f16_sdwa v183, v139 dst_sel:WORD_1 dst_unused:UNUSED_PRESERVE src0_sel:WORD_1
	v_exp_f16_sdwa v189, v179 dst_sel:WORD_1 dst_unused:UNUSED_PRESERVE src0_sel:WORD_1
	v_pk_mul_f16 v138, v183, v138
	v_pk_mul_f16 v178, v189, v178
	v_pk_max_f16 v136, v136, 0
	v_pk_max_f16 v176, v176, 0
	v_pk_fma_f16 v136, v137, v138, v136 neg_lo:[1,0,0] neg_hi:[1,0,0]
	v_pk_fma_f16 v176, v177, v178, v176 neg_lo:[1,0,0] neg_hi:[1,0,0]
	v_cvt_pk_f16_f32 v139, v28, v29
	v_cvt_pk_f16_f32 v179, v30, v31
	v_pk_mul_f16 v152, v139, v136
	v_pk_mul_f16 v153, v179, v176
	v_add_u32_e32 v152, 0x40004, v152
	v_add_u32_e32 v153, 0x40004, v153
	v_and_b32_e32 v152, 0xfff8fff8, v152
	v_and_b32_e32 v153, 0xfff8fff8, v153
	v_mov_b32_dpp v136, v146 row_ror:1 row_mask:0xf bank_mask:0xf
	v_mov_b32_dpp v176, v147 row_ror:1 row_mask:0xf bank_mask:0xf
	v_mov_b32_dpp v136, v150 row_shr:1 row_mask:0xf bank_mask:0xf
	v_mov_b32_dpp v176, v151 row_shr:1 row_mask:0xf bank_mask:0xf
	v_mov_b32_dpp v137, v142 row_ror:15 row_mask:0xf bank_mask:0xf
	v_mov_b32_dpp v177, v143 row_ror:15 row_mask:0xf bank_mask:0xf
	v_mov_b32_dpp v137, v150 row_shl:1 row_mask:0xf bank_mask:0xf
; __device__ __forceinline__ int shl_(int v, int src_lane) { return __builtin_amdgcn_ds_bpermute(src_lane << 2, v); }
;     __device__ __forceinline__ void operator()(const f32x4 (&acc)[2][2][4][2], const GUnit& u, int wr, int wc, int fr, int fq, LAS unsigned char* lds) const {
;     ...
;                 for (int m = 0; m < 4; ++m) {
;                     u32x4 UP, DN, GG;
; #pragma unroll
;                     for (int j = 0; j < 4; ++j) { const int g = (int)gp[m][j];
;                         const int oldu = m > 0 ? shl_((int)gp[m > 0 ? m - 1 : 0][j], lane15) : (int)eup[j];
;                         const int ups = __builtin_amdgcn_update_dpp(0, g, 0x111, 0xf, 0xf, true);
;                         const int oldd = m < 3 ? shl_((int)gp[m < 3 ? m + 1 : 3][j], lane0r) : (int)edp[j];
;                         const int dns = __builtin_amdgcn_update_dpp(0, g, 0x101, 0xf, 0xf, true);
;                         UP[j] = (unsigned)(frL == 0 ? oldu : ups); DN[j] = (unsigned)(frL == 15 ? oldd : dns); GG[j] = (unsigned)g; }
;                     const f16x8 uph = __builtin_bit_cast(f16x8, UP), dnh = __builtin_bit_cast(f16x8, DN), ggh = __builtin_bit_cast(f16x8, GG);
;                     f16x2 yv[4];
;                     yv[0] = __builtin_shufflevector(uph, uph, 0, 1) * w0p[0] + __builtin_shufflevector(ggh, ggh, 0, 1) * w1p[0] + __builtin_shufflevector(dnh, dnh, 0, 1) * w2p[0] + bbp[0];
;                     yv[1] = __builtin_shufflevector(uph, uph, 2, 3) * w0p[1] + __builtin_shufflevector(ggh, ggh, 2, 3) * w1p[1] + __builtin_shufflevector(dnh, dnh, 2, 3) * w2p[1] + bbp[1];
;                     yv[2] = __builtin_shufflevector(uph, uph, 4, 5) * w0p[2] + __builtin_shufflevector(ggh, ggh, 4, 5) * w1p[2] + __builtin_shufflevector(dnh, dnh, 4, 5) * w2p[2] + bbp[2];
;                     yv[3] = __builtin_shufflevector(uph, uph, 6, 7) * w0p[3] + __builtin_shufflevector(ggh, ggh, 6, 7) * w1p[3] + __builtin_shufflevector(dnh, dnh, 6, 7) * w2p[3] + bbp[3];
;                     u32x4 o;
; #pragma unroll
;                     for (int n = 0; n < 2; ++n)
; #pragma unroll
;                         for (int q = 0; q < 2; ++q) { const int j = 2 * n + q;
	v_mov_b32_dpp v177, v151 row_shl:1 row_mask:0xf bank_mask:0xf
	v_pk_fma_f16 v136, v136, v166, v162
	v_pk_fma_f16 v176, v176, v167, v163
	v_pk_fma_f16 v136, v150, v170, v136
	v_pk_fma_f16 v176, v151, v171, v176
	v_pk_fma_f16 v136, v137, v158, v136
	v_pk_fma_f16 v176, v177, v159, v176
	v_and_b32_e32 v137, 0x7fff7fff, v136
	v_and_b32_e32 v177, 0x7fff7fff, v176
	v_pk_fma_f16 v138, v137, s45, 1.0 op_sel_hi:[1,0,0]
	v_pk_fma_f16 v178, v177, s45, 1.0 op_sel_hi:[1,0,0]
	v_rcp_f16_e32 v139, v138
	v_rcp_f16_e32 v179, v178
	v_rcp_f16_sdwa v139, v138 dst_sel:WORD_1 dst_unused:UNUSED_PRESERVE src0_sel:WORD_1
	v_rcp_f16_sdwa v179, v178 dst_sel:WORD_1 dst_unused:UNUSED_PRESERVE src0_sel:WORD_1
	v_pk_fma_f16 v138, v139, s55, v228 op_sel_hi:[1,0,0]
	v_pk_fma_f16 v178, v179, s55, v228 op_sel_hi:[1,0,0]
	v_pk_fma_f16 v138, v139, v138, s65 op_sel_hi:[1,1,0]
	v_pk_fma_f16 v178, v179, v178, s65 op_sel_hi:[1,1,0]
	v_pk_fma_f16 v138, v139, v138, s68 op_sel_hi:[1,1,0]
	v_pk_fma_f16 v178, v179, v178, s68 op_sel_hi:[1,1,0]
	v_pk_fma_f16 v138, v139, v138, s69 op_sel_hi:[1,1,0]
	v_pk_fma_f16 v178, v179, v178, s69 op_sel_hi:[1,1,0]
	v_pk_mul_f16 v138, v139, v138
	v_pk_mul_f16 v178, v179, v178
	v_pk_mul_f16 v139, v136, v136
	v_pk_mul_f16 v179, v176, v176
	v_pk_mul_f16 v139, v139, s72 op_sel_hi:[1,0]
	v_pk_mul_f16 v179, v179, s72 op_sel_hi:[1,0]
	v_exp_f16_e32 v183, v139
	v_exp_f16_e32 v189, v179
	v_exp_f16_sdwa v183, v139 dst_sel:WORD_1 dst_unused:UNUSED_PRESERVE src0_sel:WORD_1
	v_exp_f16_sdwa v189, v179 dst_sel:WORD_1 dst_unused:UNUSED_PRESERVE src0_sel:WORD_1
	v_pk_mul_f16 v138, v183, v138
	v_pk_mul_f16 v178, v189, v178
	v_pk_max_f16 v136, v136, 0
	v_pk_max_f16 v176, v176, 0
	v_pk_fma_f16 v136, v137, v138, v136 neg_lo:[1,0,0] neg_hi:[1,0,0]
	v_pk_fma_f16 v176, v177, v178, v176 neg_lo:[1,0,0] neg_hi:[1,0,0]
	v_cvt_pk_f16_f32 v139, v24, v25
	v_cvt_pk_f16_f32 v179, v26, v27
	v_pk_mul_f16 v154, v139, v136
	v_pk_mul_f16 v155, v179, v176
	v_add_u32_e32 v154, 0x40004, v154
	v_add_u32_e32 v155, 0x40004, v155
	v_and_b32_e32 v154, 0xfff8fff8, v154
	v_and_b32_e32 v155, 0xfff8fff8, v155
	v_add_u32_e32 v194, 0xa0, v32
	v_mad_i64_i32 v[194:195], vcc, v194, s29, v[192:193]
	global_store_dwordx4 v[194:195], v[152:155], off
	v_mov_b32_dpp v136, v148 row_ror:1 row_mask:0xf bank_mask:0xf
	v_mov_b32_dpp v176, v150 row_ror:1 row_mask:0xf bank_mask:0xf
	v_mov_b32_dpp v136, v140 row_shr:1 row_mask:0xf bank_mask:0xf
	v_mov_b32_dpp v176, v142 row_shr:1 row_mask:0xf bank_mask:0xf
	v_mov_b32_dpp v132, v140 row_shl:1 row_mask:0xf bank_mask:0xf
	v_mov_b32_dpp v134, v142 row_shl:1 row_mask:0xf bank_mask:0xf
	v_pk_fma_f16 v136, v136, v164, v160
	v_pk_fma_f16 v176, v176, v166, v162
	v_pk_fma_f16 v136, v140, v168, v136
	v_pk_fma_f16 v176, v142, v170, v176
	v_pk_fma_f16 v136, v132, v156, v136
	v_pk_fma_f16 v176, v134, v158, v176
	v_mov_b32_dpp v137, v149 row_ror:1 row_mask:0xf bank_mask:0xf
	v_mov_b32_dpp v177, v151 row_ror:1 row_mask:0xf bank_mask:0xf
	v_mov_b32_dpp v137, v141 row_shr:1 row_mask:0xf bank_mask:0xf
	v_mov_b32_dpp v177, v143 row_shr:1 row_mask:0xf bank_mask:0xf
	v_mov_b32_dpp v133, v141 row_shl:1 row_mask:0xf bank_mask:0xf
	v_mov_b32_dpp v135, v143 row_shl:1 row_mask:0xf bank_mask:0xf
	v_pk_fma_f16 v137, v137, v165, v161
	v_pk_fma_f16 v177, v177, v167, v163
	v_pk_fma_f16 v137, v141, v169, v137
	v_pk_fma_f16 v177, v143, v171, v177
	v_pk_fma_f16 v137, v133, v157, v137
	v_pk_fma_f16 v177, v135, v159, v177
	s_cmp_lg_u32 s48, 0
	s_cbranch_scc0 .Lffn_side_bot_skip
	s_cmp_lg_u32 s36, 7
	s_cbranch_scc0 .Lffn_side_bot_skip
	s_and_saveexec_b64 s[80:81], s[8:9]
	s_lshl_b32 s12, s37, 1
	s_add_i32 s12, s12, 1
	v_mov_b32_e32 v152, 0xb00
	v_mad_i64_i32 v[152:153], vcc, s12, v152, v[190:191]
	v_readlane_b32 s12, v251, 22
	v_readlane_b32 s13, v251, 23
	v_lshlrev_b64 v[152:153], 2, v[152:153]
	s_nop 1
	v_lshl_add_u64 v[154:155], s[12:13], 0, v[152:153]
	global_store_dwordx2 v[154:155], v[4:5], off
	global_store_dwordx2 v[154:155], v[6:7], off offset:8
	global_store_dwordx2 v[154:155], v[0:1], off offset:16
	global_store_dwordx2 v[154:155], v[2:3], off offset:24
	v_readlane_b32 s12, v251, 24
	v_readlane_b32 s13, v251, 25
	v_cvt_f32_f16_e32 v138, v136
	v_cvt_f32_f16_sdwa v139, v136 dst_sel:DWORD dst_unused:UNUSED_PAD src0_sel:WORD_1
	v_lshl_add_u64 v[154:155], s[12:13], 0, v[152:153]
	global_store_dwordx2 v[154:155], v[138:139], off
	v_cvt_f32_f16_e32 v178, v137
	v_cvt_f32_f16_sdwa v179, v137 dst_sel:DWORD dst_unused:UNUSED_PAD src0_sel:WORD_1
	s_nop 0
	global_store_dwordx2 v[154:155], v[178:179], off offset:8
	v_cvt_f32_f16_e32 v138, v176
	v_cvt_f32_f16_sdwa v139, v176 dst_sel:DWORD dst_unused:UNUSED_PAD src0_sel:WORD_1
	s_nop 0
	global_store_dwordx2 v[154:155], v[138:139], off offset:16
	v_cvt_f32_f16_e32 v178, v177
	v_cvt_f32_f16_sdwa v179, v177 dst_sel:DWORD dst_unused:UNUSED_PAD src0_sel:WORD_1
	s_nop 0
	global_store_dwordx2 v[154:155], v[178:179], off offset:24
	v_readlane_b32 s12, v251, 26
	v_readlane_b32 s13, v251, 27
	s_nop 3
	v_lshl_add_u64 v[154:155], s[12:13], 0, v[152:153]
	global_store_dwordx2 v[154:155], v[12:13], off
	global_store_dwordx2 v[154:155], v[14:15], off offset:8
	global_store_dwordx2 v[154:155], v[8:9], off offset:16
	global_store_dwordx2 v[154:155], v[10:11], off offset:24
	s_or_b64 exec, exec, s[80:81]
; __device__ __forceinline__ int shl_(int v, int src_lane) { return __builtin_amdgcn_ds_bpermute(src_lane << 2, v); }
;     __device__ __forceinline__ void operator()(const f32x4 (&acc)[2][2][4][2], const GUnit& u, int wr, int wc, int fr, int fq, LAS unsigned char* lds) const {
;     ...
;                 for (int m = 0; m < 4; ++m) {
;                     u32x4 UP, DN, GG;
; #pragma unroll
;                     for (int j = 0; j < 4; ++j) { const int g = (int)gp[m][j];
;                         const int oldu = m > 0 ? shl_((int)gp[m > 0 ? m - 1 : 0][j], lane15) : (int)eup[j];
;                         const int ups = __builtin_amdgcn_update_dpp(0, g, 0x111, 0xf, 0xf, true);
;                         const int oldd = m < 3 ? shl_((int)gp[m < 3 ? m + 1 : 3][j], lane0r) : (int)edp[j];
;                         const int dns = __builtin_amdgcn_update_dpp(0, g, 0x101, 0xf, 0xf, true);
;                         UP[j] = (unsigned)(frL == 0 ? oldu : ups); DN[j] = (unsigned)(frL == 15 ? oldd : dns); GG[j] = (unsigned)g; }
;                     const f16x8 uph = __builtin_bit_cast(f16x8, UP), dnh = __builtin_bit_cast(f16x8, DN), ggh = __builtin_bit_cast(f16x8, GG);
;                     f16x2 yv[4];
;                     yv[0] = __builtin_shufflevector(uph, uph, 0, 1) * w0p[0] + __builtin_shufflevector(ggh, ggh, 0, 1) * w1p[0] + __builtin_shufflevector(dnh, dnh, 0, 1) * w2p[0] + bbp[0];
;                     yv[1] = __builtin_shufflevector(uph, uph, 2, 3) * w0p[1] + __builtin_shufflevector(ggh, ggh, 2, 3) * w1p[1] + __builtin_shufflevector(dnh, dnh, 2, 3) * w2p[1] + bbp[1];
;                     yv[2] = __builtin_shufflevector(uph, uph, 4, 5) * w0p[2] + __builtin_shufflevector(ggh, ggh, 4, 5) * w1p[2] + __builtin_shufflevector(dnh, dnh, 4, 5) * w2p[2] + bbp[2];
;                     yv[3] = __builtin_shufflevector(uph, uph, 6, 7) * w0p[3] + __builtin_shufflevector(ggh, ggh, 6, 7) * w1p[3] + __builtin_shufflevector(dnh, dnh, 6, 7) * w2p[3] + bbp[3];
;                     u32x4 o;
; #pragma unroll
;                     for (int n = 0; n < 2; ++n)
; #pragma unroll
;                         for (int q = 0; q < 2; ++q) { const int j = 2 * n + q;
.Lffn_side_bot_skip:
	v_and_b32_e32 v138, 0x7fff7fff, v136
	v_and_b32_e32 v178, 0x7fff7fff, v176
	v_pk_fma_f16 v139, v138, s45, 1.0 op_sel_hi:[1,0,0]
	v_pk_fma_f16 v179, v178, s45, 1.0 op_sel_hi:[1,0,0]
	v_rcp_f16_e32 v183, v139
	v_rcp_f16_e32 v189, v179
	v_rcp_f16_sdwa v183, v139 dst_sel:WORD_1 dst_unused:UNUSED_PRESERVE src0_sel:WORD_1
	v_rcp_f16_sdwa v189, v179 dst_sel:WORD_1 dst_unused:UNUSED_PRESERVE src0_sel:WORD_1
	v_pk_fma_f16 v139, v183, s55, v228 op_sel_hi:[1,0,0]
	v_pk_fma_f16 v179, v189, s55, v228 op_sel_hi:[1,0,0]
	v_pk_fma_f16 v139, v183, v139, s65 op_sel_hi:[1,1,0]
	v_pk_fma_f16 v179, v189, v179, s65 op_sel_hi:[1,1,0]
	v_pk_fma_f16 v139, v183, v139, s68 op_sel_hi:[1,1,0]
	v_pk_fma_f16 v179, v189, v179, s68 op_sel_hi:[1,1,0]
	v_pk_fma_f16 v139, v183, v139, s69 op_sel_hi:[1,1,0]
	v_pk_fma_f16 v179, v189, v179, s69 op_sel_hi:[1,1,0]
	v_pk_mul_f16 v139, v183, v139
	v_pk_mul_f16 v179, v189, v179
	v_pk_mul_f16 v183, v136, v136
	v_pk_mul_f16 v189, v176, v176
	v_pk_mul_f16 v183, v183, s72 op_sel_hi:[1,0]
	v_pk_mul_f16 v189, v189, s72 op_sel_hi:[1,0]
	v_exp_f16_e32 v153, v183
	v_exp_f16_e32 v155, v189
	v_exp_f16_sdwa v153, v183 dst_sel:WORD_1 dst_unused:UNUSED_PRESERVE src0_sel:WORD_1
	v_exp_f16_sdwa v155, v189 dst_sel:WORD_1 dst_unused:UNUSED_PRESERVE src0_sel:WORD_1
	v_pk_mul_f16 v139, v153, v139
	v_pk_mul_f16 v179, v155, v179
	v_pk_max_f16 v136, v136, 0
	v_pk_max_f16 v176, v176, 0
	v_pk_fma_f16 v136, v138, v139, v136 neg_lo:[1,0,0] neg_hi:[1,0,0]
	v_pk_fma_f16 v176, v178, v179, v176 neg_lo:[1,0,0] neg_hi:[1,0,0]
	v_cvt_pk_f16_f32 v183, v12, v13
	v_cvt_pk_f16_f32 v189, v8, v9
	v_pk_mul_f16 v152, v183, v136
	v_pk_mul_f16 v154, v189, v176
	v_add_u32_e32 v152, 0x40004, v152
	v_add_u32_e32 v154, 0x40004, v154
	v_and_b32_e32 v152, 0xfff8fff8, v152
	v_and_b32_e32 v154, 0xfff8fff8, v154
	v_and_b32_e32 v136, 0x7fff7fff, v137
	v_and_b32_e32 v176, 0x7fff7fff, v177
	v_pk_fma_f16 v138, v136, s45, 1.0 op_sel_hi:[1,0,0]
	v_pk_fma_f16 v178, v176, s45, 1.0 op_sel_hi:[1,0,0]
	v_rcp_f16_e32 v139, v138
	v_rcp_f16_e32 v179, v178
	v_rcp_f16_sdwa v139, v138 dst_sel:WORD_1 dst_unused:UNUSED_PRESERVE src0_sel:WORD_1
	v_rcp_f16_sdwa v179, v178 dst_sel:WORD_1 dst_unused:UNUSED_PRESERVE src0_sel:WORD_1
	v_pk_fma_f16 v138, v139, s55, v228 op_sel_hi:[1,0,0]
	v_pk_fma_f16 v178, v179, s55, v228 op_sel_hi:[1,0,0]
	v_pk_fma_f16 v138, v139, v138, s65 op_sel_hi:[1,1,0]
	v_pk_fma_f16 v178, v179, v178, s65 op_sel_hi:[1,1,0]
	v_pk_fma_f16 v138, v139, v138, s68 op_sel_hi:[1,1,0]
	v_pk_fma_f16 v178, v179, v178, s68 op_sel_hi:[1,1,0]
	v_pk_fma_f16 v138, v139, v138, s69 op_sel_hi:[1,1,0]
	v_pk_fma_f16 v178, v179, v178, s69 op_sel_hi:[1,1,0]
	v_pk_mul_f16 v138, v139, v138
	v_pk_mul_f16 v178, v179, v178
	v_pk_mul_f16 v139, v137, v137
	v_pk_mul_f16 v179, v177, v177
	v_pk_mul_f16 v139, v139, s72 op_sel_hi:[1,0]
	v_pk_mul_f16 v179, v179, s72 op_sel_hi:[1,0]
	v_exp_f16_e32 v183, v139
	v_exp_f16_e32 v189, v179
	v_exp_f16_sdwa v183, v139 dst_sel:WORD_1 dst_unused:UNUSED_PRESERVE src0_sel:WORD_1
	v_exp_f16_sdwa v189, v179 dst_sel:WORD_1 dst_unused:UNUSED_PRESERVE src0_sel:WORD_1
	v_pk_mul_f16 v138, v183, v138
	v_pk_mul_f16 v178, v189, v178
	v_pk_max_f16 v137, v137, 0
	v_pk_max_f16 v177, v177, 0
	v_pk_fma_f16 v137, v136, v138, v137 neg_lo:[1,0,0] neg_hi:[1,0,0]
	v_pk_fma_f16 v177, v176, v178, v177 neg_lo:[1,0,0] neg_hi:[1,0,0]
	v_cvt_pk_f16_f32 v139, v14, v15
	v_cvt_pk_f16_f32 v179, v10, v11
	v_pk_mul_f16 v153, v139, v137
	v_pk_mul_f16 v155, v179, v177
	v_add_u32_e32 v153, 0x40004, v153
	v_add_u32_e32 v155, 0x40004, v155
	v_and_b32_e32 v153, 0xfff8fff8, v153
	v_and_b32_e32 v155, 0xfff8fff8, v155
	v_add_u32_e32 v194, 0xb0, v32
	v_mad_i64_i32 v[194:195], vcc, v194, s29, v[192:193]
	global_store_dwordx4 v[194:195], v[152:155], off

; template <unsigned D> __device__ __forceinline__ u32x4 rd8(u32x4 w) { w.x = rd<D>(w.x); w.y = rd<D>(w.y); w.z = rd<D>(w.z); w.w = rd<D>(w.w); return w; }
; __device__ __forceinline__ u32x4 pk8(const f32x4 v0, const f32x4 v1) { u32x4 w; w.x = pk_f16(v0[0], v0[1]); w.y = pk_f16(v0[2], v0[3]); w.z = pk_f16(v1[0], v1[1]); w.w = pk_f16(v1[2], v1[3]); return w; }
;     __device__ __forceinline__ void operator()(const f32x4 (&acc)[2][2][4][2], const GUnit& u, int wr, int wc, int fr, int fq, LAS unsigned char* lds) const {
;     ...
; #pragma unroll
;                 for (int m = 0; m < 4; ++m)
; #pragma unroll
;                     for (int bj = 0; bj < 2; ++bj) { const size_t row = (size_t)(grow0 + ai * 128 + m * 16); const int col = gcol0 + bj * 128;
;                         const u32x2 gw = gwv[m][bj]; constexpr float q8 = 1.0f / 255.0f;
;                         const f32x4 g0 = {(float)(gw.x & 255u) * q8, (float)((gw.x >> 8) & 255u) * q8, (float)((gw.x >> 16) & 255u) * q8, (float)(gw.x >> 24) * q8};
;                         const f32x4 g1 = {(float)(gw.y & 255u) * q8, (float)((gw.y >> 8) & 255u) * q8, (float)((gw.y >> 16) & 255u) * q8, (float)(gw.y >> 24) * q8};
;                         f32x4 p0, p1; unpk8(pv[m][bj], p0, p1);
;                         *(u32x4*)(mrg + row * 1024 + col) = rd8<D_AMIX>(pk8(acc[ai][bj][m][0] * g0 + p0, acc[ai][bj][m][1] * g1 + p1)); }
;                 asm volatile("" ::: "memory"); }
.LBB0_422:
	s_mov_b32 s8, 0x3b808081
	s_waitcnt vmcnt(0)
	v_cvt_f32_ubyte1_e32 v211, v201
	v_cvt_f32_ubyte0_e32 v210, v201
	v_cvt_f32_ubyte3_e32 v205, v200
	v_cvt_f32_ubyte2_e32 v204, v200
	v_cvt_f32_ubyte1_e32 v207, v200
	v_cvt_f32_ubyte0_e32 v206, v200
	v_cvt_f32_ubyte3_e32 v209, v201
	v_cvt_f32_ubyte2_e32 v208, v201
	v_pk_mul_f32 v[200:201], v[210:211], s[8:9] op_sel_hi:[1,0]
	v_cvt_f32_f16_sdwa v211, v160 dst_sel:DWORD dst_unused:UNUSED_PAD src0_sel:WORD_1
	v_cvt_f32_f16_e32 v210, v160
	v_cvt_f32_f16_sdwa v213, v161 dst_sel:DWORD dst_unused:UNUSED_PAD src0_sel:WORD_1
	v_cvt_f32_f16_e32 v212, v161
	v_cvt_f32_f16_sdwa v161, v162 dst_sel:DWORD dst_unused:UNUSED_PAD src0_sel:WORD_1
	v_cvt_f32_f16_e32 v160, v162
	v_pk_mul_f32 v[206:207], v[206:207], s[8:9] op_sel_hi:[1,0]
	v_pk_mul_f32 v[204:205], v[204:205], s[8:9] op_sel_hi:[1,0]
	v_cvt_f32_f16_sdwa v215, v163 dst_sel:DWORD dst_unused:UNUSED_PAD src0_sel:WORD_1
	v_cvt_f32_f16_e32 v214, v163
	v_pk_fma_f32 v[162:163], v[66:67], v[204:205], v[212:213]
	v_pk_fma_f32 v[204:205], v[64:65], v[206:207], v[210:211]
	v_pk_mul_f32 v[208:209], v[208:209], s[8:9] op_sel_hi:[1,0]
	v_cvt_pk_f16_f32 v32, v204, v205
	v_pk_fma_f32 v[160:161], v[60:61], v[200:201], v[160:161]
	v_cvt_pk_f16_f32 v162, v162, v163
	v_add_u32_e32 v32, 0x100010, v32
	v_pk_fma_f32 v[206:207], v[62:63], v[208:209], v[214:215]
	v_cvt_pk_f16_f32 v163, v160, v161
	v_and_b32_e32 v160, 0xffe0ffe0, v32
	v_add_u32_e32 v32, 0x100010, v162
	v_cvt_pk_f16_f32 v181, v206, v207
	v_and_b32_e32 v161, 0xffe0ffe0, v32
	v_add_u32_e32 v32, 0x100010, v163
	v_and_b32_e32 v162, 0xffe0ffe0, v32
	v_add_u32_e32 v32, 0x100010, v181
	v_and_b32_e32 v163, 0xffe0ffe0, v32
	v_lshl_add_u64 v[194:195], v[194:195], 0, v[164:165]
	v_cvt_f32_ubyte1_e32 v205, v199
	v_cvt_f32_ubyte0_e32 v204, v199
	global_store_dwordx4 v[194:195], v[160:163], off
	v_cvt_f32_ubyte3_e32 v201, v199
	v_cvt_f32_ubyte2_e32 v200, v199
	v_cvt_f32_ubyte3_e32 v161, v198
	v_cvt_f32_ubyte2_e32 v160, v198
	v_cvt_f32_ubyte1_e32 v163, v198
	v_cvt_f32_ubyte0_e32 v162, v198
	v_pk_mul_f32 v[198:199], v[204:205], s[8:9] op_sel_hi:[1,0]
	v_cvt_f32_f16_sdwa v205, v156 dst_sel:DWORD dst_unused:UNUSED_PAD src0_sel:WORD_1
	v_cvt_f32_f16_e32 v204, v156
	v_cvt_f32_f16_sdwa v207, v157 dst_sel:DWORD dst_unused:UNUSED_PAD src0_sel:WORD_1
	v_cvt_f32_f16_e32 v206, v157
	v_cvt_f32_f16_sdwa v157, v158 dst_sel:DWORD dst_unused:UNUSED_PAD src0_sel:WORD_1
	v_cvt_f32_f16_e32 v156, v158
	v_pk_mul_f32 v[162:163], v[162:163], s[8:9] op_sel_hi:[1,0]
	v_pk_mul_f32 v[160:161], v[160:161], s[8:9] op_sel_hi:[1,0]
	v_cvt_f32_f16_sdwa v209, v159 dst_sel:DWORD dst_unused:UNUSED_PAD src0_sel:WORD_1
	v_cvt_f32_f16_e32 v208, v159
	v_pk_fma_f32 v[158:159], v[58:59], v[160:161], v[206:207]
	v_pk_fma_f32 v[160:161], v[56:57], v[162:163], v[204:205]
	v_pk_mul_f32 v[200:201], v[200:201], s[8:9] op_sel_hi:[1,0]
	v_cvt_pk_f16_f32 v32, v160, v161
	v_pk_fma_f32 v[156:157], v[52:53], v[198:199], v[156:157]
	v_cvt_pk_f16_f32 v158, v158, v159
	v_add_u32_e32 v32, 0x100010, v32
	v_pk_fma_f32 v[162:163], v[54:55], v[200:201], v[208:209]
	v_cvt_pk_f16_f32 v159, v156, v157
	v_and_b32_e32 v156, 0xffe0ffe0, v32
	v_add_u32_e32 v32, 0x100010, v158
	v_cvt_pk_f16_f32 v160, v162, v163
	v_and_b32_e32 v157, 0xffe0ffe0, v32
	v_add_u32_e32 v32, 0x100010, v159
	v_and_b32_e32 v158, 0xffe0ffe0, v32
	v_add_u32_e32 v32, 0x100010, v160
	v_and_b32_e32 v159, 0xffe0ffe0, v32
	global_store_dwordx4 v[194:195], v[156:159], off offset:256
	v_cvt_f32_ubyte3_e32 v161, v193
	v_cvt_f32_ubyte2_e32 v160, v193
	v_cvt_f32_ubyte3_e32 v157, v192
	v_cvt_f32_ubyte2_e32 v156, v192
	v_cvt_f32_ubyte1_e32 v159, v192
	v_cvt_f32_ubyte0_e32 v158, v192
	v_cvt_f32_ubyte1_e32 v163, v193
	v_cvt_f32_ubyte0_e32 v162, v193
	v_cvt_f32_f16_sdwa v193, v152 dst_sel:DWORD dst_unused:UNUSED_PAD src0_sel:WORD_1
	v_cvt_f32_f16_e32 v192, v152
	v_cvt_f32_f16_sdwa v195, v153 dst_sel:DWORD dst_unused:UNUSED_PAD src0_sel:WORD_1
	v_cvt_f32_f16_e32 v194, v153
	v_cvt_f32_f16_sdwa v153, v154 dst_sel:DWORD dst_unused:UNUSED_PAD src0_sel:WORD_1
	v_cvt_f32_f16_e32 v152, v154
	v_pk_mul_f32 v[158:159], v[158:159], s[8:9] op_sel_hi:[1,0]
	v_pk_mul_f32 v[156:157], v[156:157], s[8:9] op_sel_hi:[1,0]
	v_cvt_f32_f16_sdwa v199, v155 dst_sel:DWORD dst_unused:UNUSED_PAD src0_sel:WORD_1
	v_cvt_f32_f16_e32 v198, v155
	v_pk_fma_f32 v[154:155], v[50:51], v[156:157], v[194:195]
	v_pk_fma_f32 v[156:157], v[48:49], v[158:159], v[192:193]
	v_pk_mul_f32 v[162:163], v[162:163], s[8:9] op_sel_hi:[1,0]
	v_cvt_pk_f16_f32 v32, v156, v157
	v_pk_mul_f32 v[160:161], v[160:161], s[8:9] op_sel_hi:[1,0]
	v_pk_fma_f32 v[152:153], v[44:45], v[162:163], v[152:153]
	v_cvt_pk_f16_f32 v154, v154, v155
	v_add_u32_e32 v32, 0x100010, v32
	v_pk_fma_f32 v[158:159], v[46:47], v[160:161], v[198:199]
	v_cvt_pk_f16_f32 v155, v152, v153
	v_and_b32_e32 v152, 0xffe0ffe0, v32
	v_add_u32_e32 v32, 0x100010, v154
	v_cvt_pk_f16_f32 v156, v158, v159
	v_and_b32_e32 v153, 0xffe0ffe0, v32
	v_add_u32_e32 v32, 0x100010, v155
	v_and_b32_e32 v154, 0xffe0ffe0, v32
	v_add_u32_e32 v32, 0x100010, v156
	v_lshl_add_u64 v[156:157], v[178:179], 0, v[164:165]
	v_cvt_f32_f16_sdwa v163, v148 dst_sel:DWORD dst_unused:UNUSED_PAD src0_sel:WORD_1
	v_cvt_f32_f16_e32 v162, v148
	v_cvt_f32_f16_sdwa v179, v149 dst_sel:DWORD dst_unused:UNUSED_PAD src0_sel:WORD_1
	v_cvt_f32_f16_e32 v178, v149
	v_and_b32_e32 v155, 0xffe0ffe0, v32
	global_store_dwordx4 v[156:157], v[152:155], off
	v_cvt_f32_f16_sdwa v149, v150 dst_sel:DWORD dst_unused:UNUSED_PAD src0_sel:WORD_1
	v_cvt_f32_f16_e32 v148, v150
	v_cvt_f32_ubyte3_e32 v153, v190
	v_cvt_f32_ubyte2_e32 v152, v190
	v_cvt_f32_ubyte1_e32 v155, v190
; template <unsigned D> __device__ __forceinline__ u32x4 rd8(u32x4 w) { w.x = rd<D>(w.x); w.y = rd<D>(w.y); w.z = rd<D>(w.z); w.w = rd<D>(w.w); return w; }
; __device__ __forceinline__ u32x4 pk8(const f32x4 v0, const f32x4 v1) { u32x4 w; w.x = pk_f16(v0[0], v0[1]); w.y = pk_f16(v0[2], v0[3]); w.z = pk_f16(v1[0], v1[1]); w.w = pk_f16(v1[2], v1[3]); return w; }
;     __device__ __forceinline__ void operator()(const f32x4 (&acc)[2][2][4][2], const GUnit& u, int wr, int wc, int fr, int fq, LAS unsigned char* lds) const {
;     ...
; #pragma unroll
;                 for (int m = 0; m < 4; ++m)
; #pragma unroll
;                     for (int bj = 0; bj < 2; ++bj) { const size_t row = (size_t)(grow0 + ai * 128 + m * 16); const int col = gcol0 + bj * 128;
;                         const u32x2 gw = gwv[m][bj]; constexpr float q8 = 1.0f / 255.0f;
;                         const f32x4 g0 = {(float)(gw.x & 255u) * q8, (float)((gw.x >> 8) & 255u) * q8, (float)((gw.x >> 16) & 255u) * q8, (float)(gw.x >> 24) * q8};
;                         const f32x4 g1 = {(float)(gw.y & 255u) * q8, (float)((gw.y >> 8) & 255u) * q8, (float)((gw.y >> 16) & 255u) * q8, (float)(gw.y >> 24) * q8};
;                         f32x4 p0, p1; unpk8(pv[m][bj], p0, p1);
;                         *(u32x4*)(mrg + row * 1024 + col) = rd8<D_AMIX>(pk8(acc[ai][bj][m][0] * g0 + p0, acc[ai][bj][m][1] * g1 + p1)); }
;                 asm volatile("" ::: "memory"); }
	v_cvt_f32_ubyte0_e32 v154, v190
	v_pk_mul_f32 v[154:155], v[154:155], s[8:9] op_sel_hi:[1,0]
	v_pk_mul_f32 v[152:153], v[152:153], s[8:9] op_sel_hi:[1,0]
	v_cvt_f32_ubyte3_e32 v159, v191
	v_cvt_f32_ubyte2_e32 v158, v191
	v_cvt_f32_ubyte1_e32 v161, v191
	v_cvt_f32_ubyte0_e32 v160, v191
	v_cvt_f32_f16_sdwa v191, v151 dst_sel:DWORD dst_unused:UNUSED_PAD src0_sel:WORD_1
	v_cvt_f32_f16_e32 v190, v151
	v_pk_fma_f32 v[150:151], v[42:43], v[152:153], v[178:179]
	v_pk_fma_f32 v[152:153], v[40:41], v[154:155], v[162:163]
	v_pk_mul_f32 v[160:161], v[160:161], s[8:9] op_sel_hi:[1,0]
	v_cvt_pk_f16_f32 v32, v152, v153
	v_pk_mul_f32 v[158:159], v[158:159], s[8:9] op_sel_hi:[1,0]
	v_pk_fma_f32 v[148:149], v[36:37], v[160:161], v[148:149]
	v_cvt_pk_f16_f32 v150, v150, v151
	v_add_u32_e32 v32, 0x100010, v32
	v_pk_fma_f32 v[154:155], v[38:39], v[158:159], v[190:191]
	v_cvt_pk_f16_f32 v151, v148, v149
	v_and_b32_e32 v148, 0xffe0ffe0, v32
	v_add_u32_e32 v32, 0x100010, v150
	v_cvt_pk_f16_f32 v152, v154, v155
	v_and_b32_e32 v149, 0xffe0ffe0, v32
	v_add_u32_e32 v32, 0x100010, v151
	v_and_b32_e32 v150, 0xffe0ffe0, v32
	v_add_u32_e32 v32, 0x100010, v152
	v_and_b32_e32 v151, 0xffe0ffe0, v32
	global_store_dwordx4 v[156:157], v[148:151], off offset:256
	v_cvt_f32_f16_sdwa v157, v144 dst_sel:DWORD dst_unused:UNUSED_PAD src0_sel:WORD_1
	v_cvt_f32_f16_e32 v156, v144
	v_cvt_f32_f16_sdwa v159, v145 dst_sel:DWORD dst_unused:UNUSED_PAD src0_sel:WORD_1
	v_cvt_f32_f16_e32 v158, v145
	v_cvt_f32_ubyte3_e32 v149, v176
	v_cvt_f32_ubyte2_e32 v148, v176
	v_cvt_f32_ubyte1_e32 v151, v176
	v_cvt_f32_ubyte0_e32 v150, v176
	v_cvt_f32_f16_sdwa v145, v146 dst_sel:DWORD dst_unused:UNUSED_PAD src0_sel:WORD_1
	v_cvt_f32_f16_e32 v144, v146
	v_pk_mul_f32 v[150:151], v[150:151], s[8:9] op_sel_hi:[1,0]
	v_pk_mul_f32 v[148:149], v[148:149], s[8:9] op_sel_hi:[1,0]
	v_cvt_f32_f16_sdwa v161, v147 dst_sel:DWORD dst_unused:UNUSED_PAD src0_sel:WORD_1
	v_cvt_f32_f16_e32 v160, v147
	v_cvt_f32_ubyte1_e32 v155, v177
	v_cvt_f32_ubyte0_e32 v154, v177
	v_pk_fma_f32 v[146:147], v[30:31], v[148:149], v[158:159]
	v_pk_fma_f32 v[148:149], v[28:29], v[150:151], v[156:157]
	v_cvt_f32_ubyte3_e32 v153, v177
	v_cvt_f32_ubyte2_e32 v152, v177
	v_pk_mul_f32 v[154:155], v[154:155], s[8:9] op_sel_hi:[1,0]
	v_cvt_pk_f16_f32 v32, v148, v149
	v_pk_mul_f32 v[152:153], v[152:153], s[8:9] op_sel_hi:[1,0]
	v_pk_fma_f32 v[144:145], v[24:25], v[154:155], v[144:145]
	v_cvt_pk_f16_f32 v146, v146, v147
	v_add_u32_e32 v32, 0x100010, v32
	v_pk_fma_f32 v[150:151], v[26:27], v[152:153], v[160:161]
	v_cvt_pk_f16_f32 v147, v144, v145
	v_and_b32_e32 v144, 0xffe0ffe0, v32
	v_add_u32_e32 v32, 0x100010, v146
	v_cvt_pk_f16_f32 v148, v150, v151
	v_and_b32_e32 v145, 0xffe0ffe0, v32
	v_add_u32_e32 v32, 0x100010, v147
	v_and_b32_e32 v146, 0xffe0ffe0, v32
	v_add_u32_e32 v32, 0x100010, v148
	v_cvt_f32_f16_sdwa v155, v140 dst_sel:DWORD dst_unused:UNUSED_PAD src0_sel:WORD_1
	v_cvt_f32_f16_e32 v154, v140
	v_cvt_f32_f16_sdwa v157, v141 dst_sel:DWORD dst_unused:UNUSED_PAD src0_sel:WORD_1
	v_cvt_f32_f16_e32 v156, v141
	v_and_b32_e32 v147, 0xffe0ffe0, v32
	v_lshl_add_u64 v[148:149], v[172:173], 0, v[164:165]
	global_store_dwordx4 v[148:149], v[144:147], off
	v_cvt_f32_f16_sdwa v141, v142 dst_sel:DWORD dst_unused:UNUSED_PAD src0_sel:WORD_1
	v_cvt_f32_f16_e32 v140, v142
	v_cvt_f32_ubyte3_e32 v145, v174
	v_cvt_f32_ubyte2_e32 v144, v174
	v_cvt_f32_ubyte1_e32 v147, v174
	v_cvt_f32_ubyte0_e32 v146, v174
	v_pk_mul_f32 v[146:147], v[146:147], s[8:9] op_sel_hi:[1,0]
	v_pk_mul_f32 v[144:145], v[144:145], s[8:9] op_sel_hi:[1,0]
	v_cvt_f32_f16_sdwa v159, v143 dst_sel:DWORD dst_unused:UNUSED_PAD src0_sel:WORD_1
	v_cvt_f32_f16_e32 v158, v143
	v_cvt_f32_ubyte1_e32 v153, v175
	v_cvt_f32_ubyte0_e32 v152, v175
	v_pk_fma_f32 v[142:143], v[22:23], v[144:145], v[156:157]
	v_pk_fma_f32 v[144:145], v[20:21], v[146:147], v[154:155]
	v_cvt_f32_ubyte3_e32 v151, v175
	v_cvt_f32_ubyte2_e32 v150, v175
	v_pk_mul_f32 v[152:153], v[152:153], s[8:9] op_sel_hi:[1,0]
	v_cvt_pk_f16_f32 v32, v144, v145
	v_pk_mul_f32 v[150:151], v[150:151], s[8:9] op_sel_hi:[1,0]
	v_pk_fma_f32 v[140:141], v[16:17], v[152:153], v[140:141]
	v_cvt_pk_f16_f32 v142, v142, v143
	v_add_u32_e32 v32, 0x100010, v32
	v_pk_fma_f32 v[146:147], v[18:19], v[150:151], v[158:159]
	v_cvt_pk_f16_f32 v143, v140, v141
	v_and_b32_e32 v140, 0xffe0ffe0, v32
	v_add_u32_e32 v32, 0x100010, v142
	v_cvt_pk_f16_f32 v144, v146, v147
	v_and_b32_e32 v141, 0xffe0ffe0, v32
	v_add_u32_e32 v32, 0x100010, v143
	v_and_b32_e32 v142, 0xffe0ffe0, v32
	v_add_u32_e32 v32, 0x100010, v144
	v_and_b32_e32 v143, 0xffe0ffe0, v32
; #define PG8_BAR __builtin_amdgcn_s_barrier()
; template <unsigned D> __device__ __forceinline__ u32x4 rd8(u32x4 w) { w.x = rd<D>(w.x); w.y = rd<D>(w.y); w.z = rd<D>(w.z); w.w = rd<D>(w.w); return w; }
; __device__ __forceinline__ u32x4 pk8(const f32x4 v0, const f32x4 v1) { u32x4 w; w.x = pk_f16(v0[0], v0[1]); w.y = pk_f16(v0[2], v0[3]); w.z = pk_f16(v1[0], v1[1]); w.w = pk_f16(v1[2], v1[3]); return w; }
; template <bool F8 = false, class Sched, class Epi>
; __device__ __forceinline__ void gemm_phase(LAS unsigned char* lds, const Sched& S, const Epi& E) {
;     ...
;         if (!has_next) break;
;         { const bool keep = Epi::keeps_acc(cur.kind);
; #pragma unroll
;         for (int a = 0; a < 2; ++a)
; #pragma unroll
;             for (int b = 0; b < 2; ++b)
; #pragma unroll
;                 for (int m = 0; m < 4; ++m)
; #pragma unroll
;                     for (int n = 0; n < 2; ++n)
; #pragma unroll
;                         for (int e = 0; e < 4; ++e) acc[a][b][m][n][e] = keep ? acc[a][b][m][n][e] : 0.f;
;         }
;         cur = nxt; cA = nA; cB = nB; cK2 = nK2; cvA = nvA; cvB = nvB; ch64 = nh64; chs = nhs; cbhs = nbhs; ++ui;
;         if (wr == 1) PG8_BAR;
;     __device__ __forceinline__ void operator()(const f32x4 (&acc)[2][2][4][2], const GUnit& u, int wr, int wc, int fr, int fq, LAS unsigned char* lds) const {
;     ...
; #pragma unroll
;                 for (int m = 0; m < 4; ++m)
; #pragma unroll
;                     for (int bj = 0; bj < 2; ++bj) { const size_t row = (size_t)(grow0 + ai * 128 + m * 16); const int col = gcol0 + bj * 128;
;                         const u32x2 gw = gwv[m][bj]; constexpr float q8 = 1.0f / 255.0f;
;                         const f32x4 g0 = {(float)(gw.x & 255u) * q8, (float)((gw.x >> 8) & 255u) * q8, (float)((gw.x >> 16) & 255u) * q8, (float)(gw.x >> 24) * q8};
;                         const f32x4 g1 = {(float)(gw.y & 255u) * q8, (float)((gw.y >> 8) & 255u) * q8, (float)((gw.y >> 16) & 255u) * q8, (float)(gw.y >> 24) * q8};
;                         f32x4 p0, p1; unpk8(pv[m][bj], p0, p1);
;                         *(u32x4*)(mrg + row * 1024 + col) = rd8<D_AMIX>(pk8(acc[ai][bj][m][0] * g0 + p0, acc[ai][bj][m][1] * g1 + p1)); }
;                 asm volatile("" ::: "memory"); }
	global_store_dwordx4 v[148:149], v[140:143], off offset:256
	v_cvt_f32_f16_sdwa v149, v136 dst_sel:DWORD dst_unused:UNUSED_PAD src0_sel:WORD_1
	v_cvt_f32_f16_e32 v148, v136
	v_cvt_f32_f16_sdwa v151, v137 dst_sel:DWORD dst_unused:UNUSED_PAD src0_sel:WORD_1
	v_cvt_f32_f16_e32 v150, v137
	v_cvt_f32_ubyte3_e32 v141, v170
	v_cvt_f32_ubyte2_e32 v140, v170
	v_cvt_f32_ubyte1_e32 v143, v170
	v_cvt_f32_ubyte0_e32 v142, v170
	v_cvt_f32_f16_sdwa v137, v138 dst_sel:DWORD dst_unused:UNUSED_PAD src0_sel:WORD_1
	v_cvt_f32_f16_e32 v136, v138
	v_pk_mul_f32 v[142:143], v[142:143], s[8:9] op_sel_hi:[1,0]
	v_pk_mul_f32 v[140:141], v[140:141], s[8:9] op_sel_hi:[1,0]
	v_cvt_f32_f16_sdwa v153, v139 dst_sel:DWORD dst_unused:UNUSED_PAD src0_sel:WORD_1
	v_cvt_f32_f16_e32 v152, v139
	v_cvt_f32_ubyte1_e32 v147, v171
	v_cvt_f32_ubyte0_e32 v146, v171
	v_pk_fma_f32 v[138:139], v[14:15], v[140:141], v[150:151]
	v_pk_fma_f32 v[140:141], v[12:13], v[142:143], v[148:149]
	v_cvt_f32_ubyte3_e32 v145, v171
	v_cvt_f32_ubyte2_e32 v144, v171
	v_pk_mul_f32 v[146:147], v[146:147], s[8:9] op_sel_hi:[1,0]
	v_cvt_pk_f16_f32 v32, v140, v141
	v_pk_mul_f32 v[144:145], v[144:145], s[8:9] op_sel_hi:[1,0]
	v_pk_fma_f32 v[136:137], v[8:9], v[146:147], v[136:137]
	v_cvt_pk_f16_f32 v138, v138, v139
	v_add_u32_e32 v32, 0x100010, v32
	v_pk_fma_f32 v[142:143], v[10:11], v[144:145], v[152:153]
	v_cvt_pk_f16_f32 v139, v136, v137
	v_and_b32_e32 v136, 0xffe0ffe0, v32
	v_add_u32_e32 v32, 0x100010, v138
	v_cvt_pk_f16_f32 v140, v142, v143
	v_and_b32_e32 v137, 0xffe0ffe0, v32
	v_add_u32_e32 v32, 0x100010, v139
	v_and_b32_e32 v138, 0xffe0ffe0, v32
	v_add_u32_e32 v32, 0x100010, v140
	v_cvt_f32_f16_sdwa v147, v132 dst_sel:DWORD dst_unused:UNUSED_PAD src0_sel:WORD_1
	v_cvt_f32_f16_e32 v146, v132
	v_cvt_f32_f16_sdwa v149, v133 dst_sel:DWORD dst_unused:UNUSED_PAD src0_sel:WORD_1
	v_cvt_f32_f16_e32 v148, v133
	v_and_b32_e32 v139, 0xffe0ffe0, v32
	v_lshl_add_u64 v[140:141], v[166:167], 0, v[164:165]
	global_store_dwordx4 v[140:141], v[136:139], off
	v_cvt_f32_f16_sdwa v133, v134 dst_sel:DWORD dst_unused:UNUSED_PAD src0_sel:WORD_1
	v_cvt_f32_f16_e32 v132, v134
	v_cvt_f32_ubyte3_e32 v137, v168
	v_cvt_f32_ubyte2_e32 v136, v168
	v_cvt_f32_ubyte1_e32 v139, v168
	v_cvt_f32_ubyte0_e32 v138, v168
	v_pk_mul_f32 v[138:139], v[138:139], s[8:9] op_sel_hi:[1,0]
	v_pk_mul_f32 v[136:137], v[136:137], s[8:9] op_sel_hi:[1,0]
	v_cvt_f32_f16_sdwa v151, v135 dst_sel:DWORD dst_unused:UNUSED_PAD src0_sel:WORD_1
	v_cvt_f32_f16_e32 v150, v135
	v_cvt_f32_ubyte1_e32 v145, v169
	v_cvt_f32_ubyte0_e32 v144, v169
	v_pk_fma_f32 v[134:135], v[6:7], v[136:137], v[148:149]
	v_pk_fma_f32 v[136:137], v[4:5], v[138:139], v[146:147]
	v_cvt_f32_ubyte3_e32 v143, v169
	v_cvt_f32_ubyte2_e32 v142, v169
	v_pk_mul_f32 v[144:145], v[144:145], s[8:9] op_sel_hi:[1,0]
	v_cvt_pk_f16_f32 v32, v136, v137
	v_pk_mul_f32 v[142:143], v[142:143], s[8:9] op_sel_hi:[1,0]
	v_pk_fma_f32 v[132:133], v[0:1], v[144:145], v[132:133]
	v_cvt_pk_f16_f32 v134, v134, v135
	v_add_u32_e32 v32, 0x100010, v32
	v_pk_fma_f32 v[138:139], v[2:3], v[142:143], v[150:151]
	v_cvt_pk_f16_f32 v135, v132, v133
	v_and_b32_e32 v132, 0xffe0ffe0, v32
	v_add_u32_e32 v32, 0x100010, v134
	v_cvt_pk_f16_f32 v136, v138, v139
	v_and_b32_e32 v133, 0xffe0ffe0, v32
	v_add_u32_e32 v32, 0x100010, v135
	v_and_b32_e32 v134, 0xffe0ffe0, v32
	v_add_u32_e32 v32, 0x100010, v136
	v_and_b32_e32 v135, 0xffe0ffe0, v32
	global_store_dwordx4 v[140:141], v[132:135], off offset:256
	s_cbranch_execz .LBB0_299
	s_branch .LBB0_300
.LBB0_427:
	s_waitcnt vmcnt(0)
	v_readlane_b32 s66, v254, 60
	v_readlane_b32 s18, v254, 40
	v_readlane_b32 s20, v254, 43
	v_readlane_b32 s80, v254, 46
	v_readlane_b32 s74, v254, 48
	v_readlane_b32 s68, v254, 50
	v_readlane_b32 s82, v254, 53
	v_readlane_b32 s84, v254, 55
	v_readlane_b32 s26, v255, 17
	v_readlane_b32 s16, v255, 15
	s_cmp_lt_i32 s70, 11
	v_readlane_b32 s67, v254, 61
	v_readlane_b32 s92, v254, 62
	s_mov_b32 s36, s18
	v_readlane_b32 s44, v254, 42
	v_readlane_b32 s21, v254, 44
	v_readlane_b32 s50, v254, 45
	s_mov_b32 s45, s54
	v_readlane_b32 s81, v254, 47
	v_readlane_b32 s75, v254, 49
	v_readlane_b32 s69, v254, 51
	v_readlane_b32 s83, v254, 54
	v_readlane_b32 s85, v254, 56
	v_readlane_b32 s86, v254, 58
	v_readlane_b32 s87, v254, 59
	s_movk_i32 s89, 0x800
	v_readlane_b32 s90, v255, 6
	s_mov_b32 s91, s63
	v_readlane_b32 s72, v255, 21
	v_readlane_b32 s27, v255, 18
	v_readlane_b32 s17, v255, 16
	s_barrier
	v_readlane_b32 s19, v254, 41
	s_cbranch_scc1 .LBB0_429
	s_cmp_eq_u32 s70, 11
	s_mov_b64 s[4:5], 0
	s_cselect_b64 s[2:3], -1, 0
	s_branch .LBB0_430
